# scan: grouped operand prefetch (kk one step ahead of the rest) so a single per-step wait leaves two groups in flight
# speedup vs baseline: 1.0105x; 1.0000x over previous
.LBB0_685:
	ds_read_b128 v[164:167], v5 offset:0
	ds_read_b128 v[168:171], v5 offset:256
	ds_read_b128 v[172:175], v5 offset:512
	ds_read_b128 v[176:179], v5 offset:768
	ds_read_b128 v[180:183], v5 offset:1024
	ds_read_b32 v184, v9 offset:0
	ds_read_b128 v[186:189], v5 offset:1536
	ds_read_b128 v[190:193], v5 offset:1792
	ds_read_b128 v[194:197], v5 offset:2048
	ds_read_b128 v[198:201], v5 offset:2304
	ds_read_b128 v[202:205], v5 offset:2560
	ds_read_b32 v206, v9 offset:1536
	ds_read_b128 v[208:211], v5 offset:3072
	s_waitcnt lgkmcnt(12)
	v_pk_mul_f32 v[144:145], v[138:139], v[164:165]
	v_pk_fma_f32 v[144:145], v[140:141], v[166:167], v[144:145]
	v_add_f32 v146, v144, v145
	ds_read_b128 v[212:215], v5 offset:3328
	ds_read_b128 v[216:219], v5 offset:3584
	ds_read_b128 v[220:223], v5 offset:3840
	ds_read_b128 v[224:227], v5 offset:4096
	ds_read_b32 v228, v9 offset:3072
	ds_read_b128 v[230:233], v5 offset:4608
	v_add_f32_dpp v146, v146, v146 quad_perm:[1,0,3,2] row_mask:0xf bank_mask:0xf bound_ctrl:1
	s_nop 0
	s_nop 0
	v_add_f32_dpp v146, v146, v146 quad_perm:[2,3,0,1] row_mask:0xf bank_mask:0xf bound_ctrl:1
	s_waitcnt lgkmcnt(12)
	v_pk_mul_f32 v[176:177], v[176:177], v[184:185] op_sel_hi:[1,0]
	v_add_f32_dpp v146, v146, v146 row_half_mirror row_mask:0xf bank_mask:0xf bound_ctrl:1
	v_pk_mul_f32 v[178:179], v[178:179], v[184:185] op_sel_hi:[1,0]
	s_nop 0
	v_add_f32_dpp v146, v146, v146 row_mirror row_mask:0xf bank_mask:0xf bound_ctrl:1
	v_pk_fma_f32 v[176:177], v[146:147], v[168:169], v[176:177] op_sel_hi:[0,1,1] neg_lo:[1,0,0] neg_hi:[1,0,0]
	v_pk_fma_f32 v[178:179], v[146:147], v[170:171], v[178:179] op_sel_hi:[0,1,1] neg_lo:[1,0,0] neg_hi:[1,0,0]
	v_pk_fma_f32 v[138:139], v[138:139], v[172:173], v[176:177]
	v_pk_fma_f32 v[140:141], v[140:141], v[174:175], v[178:179]
	v_pk_mul_f32 v[144:145], v[138:139], v[186:187]
	v_pk_fma_f32 v[144:145], v[140:141], v[188:189], v[144:145]
	v_add_f32 v146, v144, v145
	ds_read_b128 v[234:237], v5 offset:4864
	ds_read_b128 v[238:241], v5 offset:5120
	ds_read_b128 v[242:245], v5 offset:5376
	ds_read_b128 v[246:249], v5 offset:5632
	ds_read_b32 v250, v9 offset:4608
	ds_read_b128 v[164:167], v5 offset:6144
	v_add_f32_dpp v146, v146, v146 quad_perm:[1,0,3,2] row_mask:0xf bank_mask:0xf bound_ctrl:1
	v_pk_mul_f32 v[180:181], v[138:139], v[180:181]
	v_pk_fma_f32 v[180:181], v[140:141], v[182:183], v[180:181]
	v_add_f32_dpp v146, v146, v146 quad_perm:[2,3,0,1] row_mask:0xf bank_mask:0xf bound_ctrl:1
	s_waitcnt lgkmcnt(12)
	v_pk_mul_f32 v[198:199], v[198:199], v[206:207] op_sel_hi:[1,0]
	v_add_f32_dpp v146, v146, v146 row_half_mirror row_mask:0xf bank_mask:0xf bound_ctrl:1
	v_pk_mul_f32 v[200:201], v[200:201], v[206:207] op_sel_hi:[1,0]
	v_add_f32 v148, v180, v181
	v_add_f32_dpp v146, v146, v146 row_mirror row_mask:0xf bank_mask:0xf bound_ctrl:1
	v_pk_fma_f32 v[198:199], v[146:147], v[190:191], v[198:199] op_sel_hi:[0,1,1] neg_lo:[1,0,0] neg_hi:[1,0,0]
	v_pk_fma_f32 v[200:201], v[146:147], v[192:193], v[200:201] op_sel_hi:[0,1,1] neg_lo:[1,0,0] neg_hi:[1,0,0]
	v_pk_fma_f32 v[138:139], v[138:139], v[194:195], v[198:199]
	v_pk_fma_f32 v[140:141], v[140:141], v[196:197], v[200:201]
	v_pk_mul_f32 v[144:145], v[138:139], v[208:209]
	v_pk_fma_f32 v[144:145], v[140:141], v[210:211], v[144:145]
	v_add_f32 v146, v144, v145
	ds_read_b128 v[168:171], v5 offset:6400
	ds_read_b128 v[172:175], v5 offset:6656
	ds_read_b128 v[176:179], v5 offset:6912
	ds_read_b128 v[180:183], v5 offset:7168
	ds_read_b32 v184, v9 offset:6144
	ds_read_b128 v[186:189], v5 offset:7680
	v_add_f32_dpp v146, v146, v146 quad_perm:[1,0,3,2] row_mask:0xf bank_mask:0xf bound_ctrl:1
	v_pk_mul_f32 v[202:203], v[138:139], v[202:203]
	v_pk_fma_f32 v[202:203], v[140:141], v[204:205], v[202:203]
	v_add_f32_dpp v146, v146, v146 quad_perm:[2,3,0,1] row_mask:0xf bank_mask:0xf bound_ctrl:1
	s_waitcnt lgkmcnt(12)
	v_pk_mul_f32 v[220:221], v[220:221], v[228:229] op_sel_hi:[1,0]
	v_add_f32_dpp v146, v146, v146 row_half_mirror row_mask:0xf bank_mask:0xf bound_ctrl:1
	v_pk_mul_f32 v[222:223], v[222:223], v[228:229] op_sel_hi:[1,0]
	v_add_f32 v149, v202, v203
	v_add_f32_dpp v146, v146, v146 row_mirror row_mask:0xf bank_mask:0xf bound_ctrl:1
	v_pk_fma_f32 v[220:221], v[146:147], v[212:213], v[220:221] op_sel_hi:[0,1,1] neg_lo:[1,0,0] neg_hi:[1,0,0]
	v_pk_fma_f32 v[222:223], v[146:147], v[214:215], v[222:223] op_sel_hi:[0,1,1] neg_lo:[1,0,0] neg_hi:[1,0,0]
	v_pk_fma_f32 v[138:139], v[138:139], v[216:217], v[220:221]
	v_pk_fma_f32 v[140:141], v[140:141], v[218:219], v[222:223]
	v_pk_mul_f32 v[144:145], v[138:139], v[230:231]
	v_pk_fma_f32 v[144:145], v[140:141], v[232:233], v[144:145]
	v_add_f32 v146, v144, v145
	ds_read_b128 v[190:193], v5 offset:7936
	ds_read_b128 v[194:197], v5 offset:8192
	ds_read_b128 v[198:201], v5 offset:8448
	ds_read_b128 v[202:205], v5 offset:8704
	ds_read_b32 v206, v9 offset:7680
	ds_read_b128 v[208:211], v5 offset:9216
	v_add_f32_dpp v146, v146, v146 quad_perm:[1,0,3,2] row_mask:0xf bank_mask:0xf bound_ctrl:1
	v_pk_mul_f32 v[224:225], v[138:139], v[224:225]
	v_pk_fma_f32 v[224:225], v[140:141], v[226:227], v[224:225]
	v_add_f32_dpp v146, v146, v146 quad_perm:[2,3,0,1] row_mask:0xf bank_mask:0xf bound_ctrl:1
	s_waitcnt lgkmcnt(12)
	v_pk_mul_f32 v[242:243], v[242:243], v[250:251] op_sel_hi:[1,0]
	v_add_f32_dpp v146, v146, v146 row_half_mirror row_mask:0xf bank_mask:0xf bound_ctrl:1
	v_pk_mul_f32 v[244:245], v[244:245], v[250:251] op_sel_hi:[1,0]
	v_add_f32 v150, v224, v225
	v_add_f32_dpp v146, v146, v146 row_mirror row_mask:0xf bank_mask:0xf bound_ctrl:1
	v_pk_fma_f32 v[242:243], v[146:147], v[234:235], v[242:243] op_sel_hi:[0,1,1] neg_lo:[1,0,0] neg_hi:[1,0,0]
	v_pk_fma_f32 v[244:245], v[146:147], v[236:237], v[244:245] op_sel_hi:[0,1,1] neg_lo:[1,0,0] neg_hi:[1,0,0]
	v_pk_fma_f32 v[138:139], v[138:139], v[238:239], v[242:243]
	v_pk_fma_f32 v[140:141], v[140:141], v[240:241], v[244:245]
	v_pk_mul_f32 v[144:145], v[138:139], v[164:165]
	v_pk_fma_f32 v[144:145], v[140:141], v[166:167], v[144:145]
	v_add_f32 v146, v144, v145
	ds_read_b128 v[212:215], v5 offset:9472
	ds_read_b128 v[216:219], v5 offset:9728
	ds_read_b128 v[220:223], v5 offset:9984
	ds_read_b128 v[224:227], v5 offset:10240
	ds_read_b32 v228, v9 offset:9216
	ds_read_b128 v[230:233], v5 offset:10752
	v_add_f32_dpp v146, v146, v146 quad_perm:[1,0,3,2] row_mask:0xf bank_mask:0xf bound_ctrl:1
	v_pk_mul_f32 v[246:247], v[138:139], v[246:247]
	v_pk_fma_f32 v[246:247], v[140:141], v[248:249], v[246:247]
	v_add_f32_dpp v146, v146, v146 quad_perm:[2,3,0,1] row_mask:0xf bank_mask:0xf bound_ctrl:1
	s_waitcnt lgkmcnt(12)
	v_pk_mul_f32 v[176:177], v[176:177], v[184:185] op_sel_hi:[1,0]
	v_add_f32_dpp v146, v146, v146 row_half_mirror row_mask:0xf bank_mask:0xf bound_ctrl:1
	v_pk_mul_f32 v[178:179], v[178:179], v[184:185] op_sel_hi:[1,0]
	v_add_f32 v151, v246, v247
	v_add_f32_dpp v146, v146, v146 row_mirror row_mask:0xf bank_mask:0xf bound_ctrl:1
	v_pk_fma_f32 v[176:177], v[146:147], v[168:169], v[176:177] op_sel_hi:[0,1,1] neg_lo:[1,0,0] neg_hi:[1,0,0]
	v_pk_fma_f32 v[178:179], v[146:147], v[170:171], v[178:179] op_sel_hi:[0,1,1] neg_lo:[1,0,0] neg_hi:[1,0,0]
	v_pk_fma_f32 v[138:139], v[138:139], v[172:173], v[176:177]
	v_pk_fma_f32 v[140:141], v[140:141], v[174:175], v[178:179]
	v_pk_mul_f32 v[144:145], v[138:139], v[186:187]
	v_pk_fma_f32 v[144:145], v[140:141], v[188:189], v[144:145]
	v_add_f32 v146, v144, v145
	ds_read_b128 v[234:237], v5 offset:11008
	ds_read_b128 v[238:241], v5 offset:11264
	ds_read_b128 v[242:245], v5 offset:11520
	ds_read_b128 v[246:249], v5 offset:11776
	ds_read_b32 v250, v9 offset:10752
	ds_read_b128 v[164:167], v5 offset:12288
	v_add_f32_dpp v146, v146, v146 quad_perm:[1,0,3,2] row_mask:0xf bank_mask:0xf bound_ctrl:1
	v_pk_mul_f32 v[180:181], v[138:139], v[180:181]
	v_pk_fma_f32 v[180:181], v[140:141], v[182:183], v[180:181]
	v_add_f32_dpp v146, v146, v146 quad_perm:[2,3,0,1] row_mask:0xf bank_mask:0xf bound_ctrl:1
	s_waitcnt lgkmcnt(12)
	v_pk_mul_f32 v[198:199], v[198:199], v[206:207] op_sel_hi:[1,0]
	v_add_f32_dpp v146, v146, v146 row_half_mirror row_mask:0xf bank_mask:0xf bound_ctrl:1
	v_pk_mul_f32 v[200:201], v[200:201], v[206:207] op_sel_hi:[1,0]
	v_add_f32 v152, v180, v181
	v_add_f32_dpp v146, v146, v146 row_mirror row_mask:0xf bank_mask:0xf bound_ctrl:1
	v_pk_fma_f32 v[198:199], v[146:147], v[190:191], v[198:199] op_sel_hi:[0,1,1] neg_lo:[1,0,0] neg_hi:[1,0,0]
	v_pk_fma_f32 v[200:201], v[146:147], v[192:193], v[200:201] op_sel_hi:[0,1,1] neg_lo:[1,0,0] neg_hi:[1,0,0]
	v_pk_fma_f32 v[138:139], v[138:139], v[194:195], v[198:199]
	v_pk_fma_f32 v[140:141], v[140:141], v[196:197], v[200:201]
	v_pk_mul_f32 v[144:145], v[138:139], v[208:209]
	v_pk_fma_f32 v[144:145], v[140:141], v[210:211], v[144:145]
	v_add_f32 v146, v144, v145
	ds_read_b128 v[168:171], v5 offset:12544
	ds_read_b128 v[172:175], v5 offset:12800
	ds_read_b128 v[176:179], v5 offset:13056
	ds_read_b128 v[180:183], v5 offset:13312
	ds_read_b32 v184, v9 offset:12288
	ds_read_b128 v[186:189], v5 offset:13824
	v_add_f32_dpp v146, v146, v146 quad_perm:[1,0,3,2] row_mask:0xf bank_mask:0xf bound_ctrl:1
	v_pk_mul_f32 v[202:203], v[138:139], v[202:203]
	v_pk_fma_f32 v[202:203], v[140:141], v[204:205], v[202:203]
	v_add_f32_dpp v146, v146, v146 quad_perm:[2,3,0,1] row_mask:0xf bank_mask:0xf bound_ctrl:1
	s_waitcnt lgkmcnt(12)
	v_pk_mul_f32 v[220:221], v[220:221], v[228:229] op_sel_hi:[1,0]
	v_add_f32_dpp v146, v146, v146 row_half_mirror row_mask:0xf bank_mask:0xf bound_ctrl:1
	v_pk_mul_f32 v[222:223], v[222:223], v[228:229] op_sel_hi:[1,0]
	v_add_f32 v153, v202, v203
	v_add_f32_dpp v146, v146, v146 row_mirror row_mask:0xf bank_mask:0xf bound_ctrl:1
	v_pk_fma_f32 v[220:221], v[146:147], v[212:213], v[220:221] op_sel_hi:[0,1,1] neg_lo:[1,0,0] neg_hi:[1,0,0]
	v_pk_fma_f32 v[222:223], v[146:147], v[214:215], v[222:223] op_sel_hi:[0,1,1] neg_lo:[1,0,0] neg_hi:[1,0,0]
	v_pk_fma_f32 v[138:139], v[138:139], v[216:217], v[220:221]
	v_pk_fma_f32 v[140:141], v[140:141], v[218:219], v[222:223]
	v_pk_mul_f32 v[144:145], v[138:139], v[230:231]
	v_pk_fma_f32 v[144:145], v[140:141], v[232:233], v[144:145]
	v_add_f32 v146, v144, v145
	ds_read_b128 v[190:193], v5 offset:14080
	ds_read_b128 v[194:197], v5 offset:14336
	ds_read_b128 v[198:201], v5 offset:14592
	ds_read_b128 v[202:205], v5 offset:14848
	ds_read_b32 v206, v9 offset:13824
	ds_read_b128 v[208:211], v5 offset:15360
	v_add_f32_dpp v146, v146, v146 quad_perm:[1,0,3,2] row_mask:0xf bank_mask:0xf bound_ctrl:1
	v_pk_mul_f32 v[224:225], v[138:139], v[224:225]
	v_pk_fma_f32 v[224:225], v[140:141], v[226:227], v[224:225]
	v_add_f32_dpp v146, v146, v146 quad_perm:[2,3,0,1] row_mask:0xf bank_mask:0xf bound_ctrl:1
	s_waitcnt lgkmcnt(12)
	v_pk_mul_f32 v[242:243], v[242:243], v[250:251] op_sel_hi:[1,0]
	v_add_f32_dpp v146, v146, v146 row_half_mirror row_mask:0xf bank_mask:0xf bound_ctrl:1
	v_pk_mul_f32 v[244:245], v[244:245], v[250:251] op_sel_hi:[1,0]
	v_add_f32 v154, v224, v225
	v_add_f32_dpp v146, v146, v146 row_mirror row_mask:0xf bank_mask:0xf bound_ctrl:1
	v_pk_fma_f32 v[242:243], v[146:147], v[234:235], v[242:243] op_sel_hi:[0,1,1] neg_lo:[1,0,0] neg_hi:[1,0,0]
	v_pk_fma_f32 v[244:245], v[146:147], v[236:237], v[244:245] op_sel_hi:[0,1,1] neg_lo:[1,0,0] neg_hi:[1,0,0]
	v_pk_fma_f32 v[138:139], v[138:139], v[238:239], v[242:243]
	v_pk_fma_f32 v[140:141], v[140:141], v[240:241], v[244:245]
	v_pk_mul_f32 v[144:145], v[138:139], v[164:165]
	v_pk_fma_f32 v[144:145], v[140:141], v[166:167], v[144:145]
	v_add_f32 v146, v144, v145
	ds_read_b128 v[212:215], v5 offset:15616
	ds_read_b128 v[216:219], v5 offset:15872
	ds_read_b128 v[220:223], v5 offset:16128
	ds_read_b128 v[224:227], v5 offset:16384
	ds_read_b32 v228, v9 offset:15360
	ds_read_b128 v[230:233], v5 offset:16896
	v_add_f32_dpp v146, v146, v146 quad_perm:[1,0,3,2] row_mask:0xf bank_mask:0xf bound_ctrl:1
	v_pk_mul_f32 v[246:247], v[138:139], v[246:247]
	v_pk_fma_f32 v[246:247], v[140:141], v[248:249], v[246:247]
	v_add_f32_dpp v146, v146, v146 quad_perm:[2,3,0,1] row_mask:0xf bank_mask:0xf bound_ctrl:1
	s_waitcnt lgkmcnt(12)
	v_pk_mul_f32 v[176:177], v[176:177], v[184:185] op_sel_hi:[1,0]
	v_add_f32_dpp v146, v146, v146 row_half_mirror row_mask:0xf bank_mask:0xf bound_ctrl:1
	v_pk_mul_f32 v[178:179], v[178:179], v[184:185] op_sel_hi:[1,0]
	v_add_f32 v155, v246, v247
	v_add_f32_dpp v146, v146, v146 row_mirror row_mask:0xf bank_mask:0xf bound_ctrl:1
	v_pk_fma_f32 v[176:177], v[146:147], v[168:169], v[176:177] op_sel_hi:[0,1,1] neg_lo:[1,0,0] neg_hi:[1,0,0]
	v_pk_fma_f32 v[178:179], v[146:147], v[170:171], v[178:179] op_sel_hi:[0,1,1] neg_lo:[1,0,0] neg_hi:[1,0,0]
	v_pk_fma_f32 v[138:139], v[138:139], v[172:173], v[176:177]
	v_pk_fma_f32 v[140:141], v[140:141], v[174:175], v[178:179]
	v_pk_mul_f32 v[144:145], v[138:139], v[186:187]
	v_pk_fma_f32 v[144:145], v[140:141], v[188:189], v[144:145]
	v_add_f32 v146, v144, v145
	ds_read_b128 v[234:237], v5 offset:17152
	ds_read_b128 v[238:241], v5 offset:17408
	ds_read_b128 v[242:245], v5 offset:17664
	ds_read_b128 v[246:249], v5 offset:17920
	ds_read_b32 v250, v9 offset:16896
	ds_read_b128 v[164:167], v5 offset:18432
	v_add_f32_dpp v146, v146, v146 quad_perm:[1,0,3,2] row_mask:0xf bank_mask:0xf bound_ctrl:1
	v_pk_mul_f32 v[180:181], v[138:139], v[180:181]
	v_pk_fma_f32 v[180:181], v[140:141], v[182:183], v[180:181]
	v_add_f32_dpp v146, v146, v146 quad_perm:[2,3,0,1] row_mask:0xf bank_mask:0xf bound_ctrl:1
	s_waitcnt lgkmcnt(12)
	v_pk_mul_f32 v[198:199], v[198:199], v[206:207] op_sel_hi:[1,0]
	v_add_f32_dpp v146, v146, v146 row_half_mirror row_mask:0xf bank_mask:0xf bound_ctrl:1
	v_pk_mul_f32 v[200:201], v[200:201], v[206:207] op_sel_hi:[1,0]
	v_add_f32 v156, v180, v181
	v_add_f32_dpp v146, v146, v146 row_mirror row_mask:0xf bank_mask:0xf bound_ctrl:1
	v_pk_fma_f32 v[198:199], v[146:147], v[190:191], v[198:199] op_sel_hi:[0,1,1] neg_lo:[1,0,0] neg_hi:[1,0,0]
	v_pk_fma_f32 v[200:201], v[146:147], v[192:193], v[200:201] op_sel_hi:[0,1,1] neg_lo:[1,0,0] neg_hi:[1,0,0]
	v_pk_fma_f32 v[138:139], v[138:139], v[194:195], v[198:199]
	v_pk_fma_f32 v[140:141], v[140:141], v[196:197], v[200:201]
	v_pk_mul_f32 v[144:145], v[138:139], v[208:209]
	v_pk_fma_f32 v[144:145], v[140:141], v[210:211], v[144:145]
	v_add_f32 v146, v144, v145
	ds_read_b128 v[168:171], v5 offset:18688
	ds_read_b128 v[172:175], v5 offset:18944
	ds_read_b128 v[176:179], v5 offset:19200
	ds_read_b128 v[180:183], v5 offset:19456
	ds_read_b32 v184, v9 offset:18432
	ds_read_b128 v[186:189], v5 offset:19968
	v_add_f32_dpp v146, v146, v146 quad_perm:[1,0,3,2] row_mask:0xf bank_mask:0xf bound_ctrl:1
	v_pk_mul_f32 v[202:203], v[138:139], v[202:203]
	v_pk_fma_f32 v[202:203], v[140:141], v[204:205], v[202:203]
	v_add_f32_dpp v146, v146, v146 quad_perm:[2,3,0,1] row_mask:0xf bank_mask:0xf bound_ctrl:1
	s_waitcnt lgkmcnt(12)
	v_pk_mul_f32 v[220:221], v[220:221], v[228:229] op_sel_hi:[1,0]
	v_add_f32_dpp v146, v146, v146 row_half_mirror row_mask:0xf bank_mask:0xf bound_ctrl:1
	v_pk_mul_f32 v[222:223], v[222:223], v[228:229] op_sel_hi:[1,0]
	v_add_f32 v157, v202, v203
	v_add_f32_dpp v146, v146, v146 row_mirror row_mask:0xf bank_mask:0xf bound_ctrl:1
	v_pk_fma_f32 v[220:221], v[146:147], v[212:213], v[220:221] op_sel_hi:[0,1,1] neg_lo:[1,0,0] neg_hi:[1,0,0]
	v_pk_fma_f32 v[222:223], v[146:147], v[214:215], v[222:223] op_sel_hi:[0,1,1] neg_lo:[1,0,0] neg_hi:[1,0,0]
	v_pk_fma_f32 v[138:139], v[138:139], v[216:217], v[220:221]
	v_pk_fma_f32 v[140:141], v[140:141], v[218:219], v[222:223]
	v_pk_mul_f32 v[144:145], v[138:139], v[230:231]
	v_pk_fma_f32 v[144:145], v[140:141], v[232:233], v[144:145]
	v_add_f32 v146, v144, v145
	ds_read_b128 v[190:193], v5 offset:20224
	ds_read_b128 v[194:197], v5 offset:20480
	ds_read_b128 v[198:201], v5 offset:20736
	ds_read_b128 v[202:205], v5 offset:20992
	ds_read_b32 v206, v9 offset:19968
	ds_read_b128 v[208:211], v5 offset:21504
	v_add_f32_dpp v146, v146, v146 quad_perm:[1,0,3,2] row_mask:0xf bank_mask:0xf bound_ctrl:1
	v_pk_mul_f32 v[224:225], v[138:139], v[224:225]
	v_pk_fma_f32 v[224:225], v[140:141], v[226:227], v[224:225]
	v_add_f32_dpp v146, v146, v146 quad_perm:[2,3,0,1] row_mask:0xf bank_mask:0xf bound_ctrl:1
	s_waitcnt lgkmcnt(12)
	v_pk_mul_f32 v[242:243], v[242:243], v[250:251] op_sel_hi:[1,0]
	v_add_f32_dpp v146, v146, v146 row_half_mirror row_mask:0xf bank_mask:0xf bound_ctrl:1
	v_pk_mul_f32 v[244:245], v[244:245], v[250:251] op_sel_hi:[1,0]
	v_add_f32 v158, v224, v225
	v_add_f32_dpp v146, v146, v146 row_mirror row_mask:0xf bank_mask:0xf bound_ctrl:1
	v_pk_fma_f32 v[242:243], v[146:147], v[234:235], v[242:243] op_sel_hi:[0,1,1] neg_lo:[1,0,0] neg_hi:[1,0,0]
	v_pk_fma_f32 v[244:245], v[146:147], v[236:237], v[244:245] op_sel_hi:[0,1,1] neg_lo:[1,0,0] neg_hi:[1,0,0]
	v_pk_fma_f32 v[138:139], v[138:139], v[238:239], v[242:243]
	v_pk_fma_f32 v[140:141], v[140:141], v[240:241], v[244:245]
	v_pk_mul_f32 v[144:145], v[138:139], v[164:165]
	v_pk_fma_f32 v[144:145], v[140:141], v[166:167], v[144:145]
	v_add_f32 v146, v144, v145
	ds_read_b128 v[212:215], v5 offset:21760
	ds_read_b128 v[216:219], v5 offset:22016
	ds_read_b128 v[220:223], v5 offset:22272
	ds_read_b128 v[224:227], v5 offset:22528
	ds_read_b32 v228, v9 offset:21504
	ds_read_b128 v[230:233], v5 offset:23040
	v_add_f32_dpp v146, v146, v146 quad_perm:[1,0,3,2] row_mask:0xf bank_mask:0xf bound_ctrl:1
	v_pk_mul_f32 v[246:247], v[138:139], v[246:247]
	v_pk_fma_f32 v[246:247], v[140:141], v[248:249], v[246:247]
	v_add_f32_dpp v146, v146, v146 quad_perm:[2,3,0,1] row_mask:0xf bank_mask:0xf bound_ctrl:1
	s_waitcnt lgkmcnt(12)
	v_pk_mul_f32 v[176:177], v[176:177], v[184:185] op_sel_hi:[1,0]
	v_add_f32_dpp v146, v146, v146 row_half_mirror row_mask:0xf bank_mask:0xf bound_ctrl:1
	v_pk_mul_f32 v[178:179], v[178:179], v[184:185] op_sel_hi:[1,0]
	v_add_f32 v159, v246, v247
	v_add_f32_dpp v146, v146, v146 row_mirror row_mask:0xf bank_mask:0xf bound_ctrl:1
	v_pk_fma_f32 v[176:177], v[146:147], v[168:169], v[176:177] op_sel_hi:[0,1,1] neg_lo:[1,0,0] neg_hi:[1,0,0]
	v_pk_fma_f32 v[178:179], v[146:147], v[170:171], v[178:179] op_sel_hi:[0,1,1] neg_lo:[1,0,0] neg_hi:[1,0,0]
	v_pk_fma_f32 v[138:139], v[138:139], v[172:173], v[176:177]
	v_pk_fma_f32 v[140:141], v[140:141], v[174:175], v[178:179]
	v_pk_mul_f32 v[144:145], v[138:139], v[186:187]
	v_pk_fma_f32 v[144:145], v[140:141], v[188:189], v[144:145]
	v_add_f32 v146, v144, v145
	ds_read_b128 v[234:237], v5 offset:23296
	ds_read_b128 v[238:241], v5 offset:23552
	ds_read_b128 v[242:245], v5 offset:23808
	ds_read_b128 v[246:249], v5 offset:24064
	ds_read_b32 v250, v9 offset:23040
	ds_read_b128 v[164:167], v5 offset:24576
	v_add_f32_dpp v146, v146, v146 quad_perm:[1,0,3,2] row_mask:0xf bank_mask:0xf bound_ctrl:1
	v_pk_mul_f32 v[180:181], v[138:139], v[180:181]
	v_pk_fma_f32 v[180:181], v[140:141], v[182:183], v[180:181]
	v_add_f32_dpp v146, v146, v146 quad_perm:[2,3,0,1] row_mask:0xf bank_mask:0xf bound_ctrl:1
	s_waitcnt lgkmcnt(12)
	v_pk_mul_f32 v[198:199], v[198:199], v[206:207] op_sel_hi:[1,0]
	v_add_f32_dpp v146, v146, v146 row_half_mirror row_mask:0xf bank_mask:0xf bound_ctrl:1
	v_pk_mul_f32 v[200:201], v[200:201], v[206:207] op_sel_hi:[1,0]
	v_add_f32 v160, v180, v181
	v_add_f32_dpp v146, v146, v146 row_mirror row_mask:0xf bank_mask:0xf bound_ctrl:1
	v_pk_fma_f32 v[198:199], v[146:147], v[190:191], v[198:199] op_sel_hi:[0,1,1] neg_lo:[1,0,0] neg_hi:[1,0,0]
	v_pk_fma_f32 v[200:201], v[146:147], v[192:193], v[200:201] op_sel_hi:[0,1,1] neg_lo:[1,0,0] neg_hi:[1,0,0]
	v_pk_fma_f32 v[138:139], v[138:139], v[194:195], v[198:199]
	v_pk_fma_f32 v[140:141], v[140:141], v[196:197], v[200:201]
	v_pk_mul_f32 v[144:145], v[138:139], v[208:209]
	v_pk_fma_f32 v[144:145], v[140:141], v[210:211], v[144:145]
	v_add_f32 v146, v144, v145
	ds_read_b128 v[168:171], v5 offset:24832
	ds_read_b128 v[172:175], v5 offset:25088
	ds_read_b128 v[176:179], v5 offset:25344
	ds_read_b128 v[180:183], v5 offset:25600
	ds_read_b32 v184, v9 offset:24576
	ds_read_b128 v[186:189], v5 offset:26112
	v_add_f32_dpp v146, v146, v146 quad_perm:[1,0,3,2] row_mask:0xf bank_mask:0xf bound_ctrl:1
	v_pk_mul_f32 v[202:203], v[138:139], v[202:203]
	v_pk_fma_f32 v[202:203], v[140:141], v[204:205], v[202:203]
	v_add_f32_dpp v146, v146, v146 quad_perm:[2,3,0,1] row_mask:0xf bank_mask:0xf bound_ctrl:1
	s_waitcnt lgkmcnt(12)
	v_pk_mul_f32 v[220:221], v[220:221], v[228:229] op_sel_hi:[1,0]
	v_add_f32_dpp v146, v146, v146 row_half_mirror row_mask:0xf bank_mask:0xf bound_ctrl:1
	v_pk_mul_f32 v[222:223], v[222:223], v[228:229] op_sel_hi:[1,0]
	v_add_f32 v161, v202, v203
	v_add_f32_dpp v146, v146, v146 row_mirror row_mask:0xf bank_mask:0xf bound_ctrl:1
	v_pk_fma_f32 v[220:221], v[146:147], v[212:213], v[220:221] op_sel_hi:[0,1,1] neg_lo:[1,0,0] neg_hi:[1,0,0]
	v_pk_fma_f32 v[222:223], v[146:147], v[214:215], v[222:223] op_sel_hi:[0,1,1] neg_lo:[1,0,0] neg_hi:[1,0,0]
	v_pk_fma_f32 v[138:139], v[138:139], v[216:217], v[220:221]
	v_pk_fma_f32 v[140:141], v[140:141], v[218:219], v[222:223]
	v_pk_mul_f32 v[144:145], v[138:139], v[230:231]
	v_pk_fma_f32 v[144:145], v[140:141], v[232:233], v[144:145]
	v_add_f32 v146, v144, v145
	ds_read_b128 v[190:193], v5 offset:26368
	ds_read_b128 v[194:197], v5 offset:26624
	ds_read_b128 v[198:201], v5 offset:26880
	ds_read_b128 v[202:205], v5 offset:27136
	ds_read_b32 v206, v9 offset:26112
	ds_read_b128 v[208:211], v5 offset:27648
	v_add_f32_dpp v146, v146, v146 quad_perm:[1,0,3,2] row_mask:0xf bank_mask:0xf bound_ctrl:1
	v_pk_mul_f32 v[224:225], v[138:139], v[224:225]
	v_pk_fma_f32 v[224:225], v[140:141], v[226:227], v[224:225]
	v_add_f32_dpp v146, v146, v146 quad_perm:[2,3,0,1] row_mask:0xf bank_mask:0xf bound_ctrl:1
	s_waitcnt lgkmcnt(12)
	v_pk_mul_f32 v[242:243], v[242:243], v[250:251] op_sel_hi:[1,0]
	v_add_f32_dpp v146, v146, v146 row_half_mirror row_mask:0xf bank_mask:0xf bound_ctrl:1
	v_pk_mul_f32 v[244:245], v[244:245], v[250:251] op_sel_hi:[1,0]
	v_add_f32 v162, v224, v225
	v_add_f32_dpp v146, v146, v146 row_mirror row_mask:0xf bank_mask:0xf bound_ctrl:1
	v_pk_fma_f32 v[242:243], v[146:147], v[234:235], v[242:243] op_sel_hi:[0,1,1] neg_lo:[1,0,0] neg_hi:[1,0,0]
	v_pk_fma_f32 v[244:245], v[146:147], v[236:237], v[244:245] op_sel_hi:[0,1,1] neg_lo:[1,0,0] neg_hi:[1,0,0]
	v_pk_fma_f32 v[138:139], v[138:139], v[238:239], v[242:243]
	v_pk_fma_f32 v[140:141], v[140:141], v[240:241], v[244:245]
	v_pk_mul_f32 v[144:145], v[138:139], v[164:165]
	v_pk_fma_f32 v[144:145], v[140:141], v[166:167], v[144:145]
	v_add_f32 v146, v144, v145
	ds_read_b128 v[212:215], v5 offset:27904
	ds_read_b128 v[216:219], v5 offset:28160
	ds_read_b128 v[220:223], v5 offset:28416
	ds_read_b128 v[224:227], v5 offset:28672
	ds_read_b32 v228, v9 offset:27648
	ds_read_b128 v[230:233], v5 offset:29184
	v_add_f32_dpp v146, v146, v146 quad_perm:[1,0,3,2] row_mask:0xf bank_mask:0xf bound_ctrl:1
	v_pk_mul_f32 v[246:247], v[138:139], v[246:247]
	v_pk_fma_f32 v[246:247], v[140:141], v[248:249], v[246:247]
	v_add_f32_dpp v146, v146, v146 quad_perm:[2,3,0,1] row_mask:0xf bank_mask:0xf bound_ctrl:1
	s_waitcnt lgkmcnt(12)
	v_pk_mul_f32 v[176:177], v[176:177], v[184:185] op_sel_hi:[1,0]
	v_add_f32_dpp v146, v146, v146 row_half_mirror row_mask:0xf bank_mask:0xf bound_ctrl:1
	v_pk_mul_f32 v[178:179], v[178:179], v[184:185] op_sel_hi:[1,0]
	v_add_f32 v163, v246, v247
	v_add_f32_dpp v146, v146, v146 row_mirror row_mask:0xf bank_mask:0xf bound_ctrl:1
	v_pk_fma_f32 v[176:177], v[146:147], v[168:169], v[176:177] op_sel_hi:[0,1,1] neg_lo:[1,0,0] neg_hi:[1,0,0]
	v_pk_fma_f32 v[178:179], v[146:147], v[170:171], v[178:179] op_sel_hi:[0,1,1] neg_lo:[1,0,0] neg_hi:[1,0,0]
	v_pk_fma_f32 v[138:139], v[138:139], v[172:173], v[176:177]
	v_pk_fma_f32 v[140:141], v[140:141], v[174:175], v[178:179]
	v_pk_mul_f32 v[144:145], v[138:139], v[186:187]
	v_pk_fma_f32 v[144:145], v[140:141], v[188:189], v[144:145]
	v_add_f32 v146, v144, v145
	v_add_f32_dpp v102, v148, v148 row_mirror row_mask:0xf bank_mask:0x3 bound_ctrl:1
	v_add_f32_dpp v102, v156, v156 row_mirror row_mask:0xf bank_mask:0xc bound_ctrl:1
	v_add_f32_dpp v103, v149, v149 row_mirror row_mask:0xf bank_mask:0x3 bound_ctrl:1
	v_add_f32_dpp v103, v157, v157 row_mirror row_mask:0xf bank_mask:0xc bound_ctrl:1
	v_add_f32_dpp v104, v150, v150 row_mirror row_mask:0xf bank_mask:0x3 bound_ctrl:1
	v_add_f32_dpp v104, v158, v158 row_mirror row_mask:0xf bank_mask:0xc bound_ctrl:1
	v_add_f32_dpp v105, v151, v151 row_mirror row_mask:0xf bank_mask:0x3 bound_ctrl:1
	v_add_f32_dpp v105, v159, v159 row_mirror row_mask:0xf bank_mask:0xc bound_ctrl:1
	v_add_f32_dpp v106, v152, v152 row_mirror row_mask:0xf bank_mask:0x3 bound_ctrl:1
	v_add_f32_dpp v106, v160, v160 row_mirror row_mask:0xf bank_mask:0xc bound_ctrl:1
	v_add_f32_dpp v107, v153, v153 row_mirror row_mask:0xf bank_mask:0x3 bound_ctrl:1
	v_add_f32_dpp v107, v161, v161 row_mirror row_mask:0xf bank_mask:0xc bound_ctrl:1
	v_add_f32_dpp v108, v154, v154 row_mirror row_mask:0xf bank_mask:0x3 bound_ctrl:1
	v_add_f32_dpp v108, v162, v162 row_mirror row_mask:0xf bank_mask:0xc bound_ctrl:1
	v_add_f32_dpp v109, v155, v155 row_mirror row_mask:0xf bank_mask:0x3 bound_ctrl:1
	v_add_f32_dpp v109, v163, v163 row_mirror row_mask:0xf bank_mask:0xc bound_ctrl:1
	v_add_f32_dpp v110, v102, v102 row_half_mirror row_mask:0xf bank_mask:0x5 bound_ctrl:1
	v_add_f32_dpp v110, v106, v106 row_half_mirror row_mask:0xf bank_mask:0xa bound_ctrl:1
	v_add_f32_dpp v111, v103, v103 row_half_mirror row_mask:0xf bank_mask:0x5 bound_ctrl:1
	v_add_f32_dpp v111, v107, v107 row_half_mirror row_mask:0xf bank_mask:0xa bound_ctrl:1
	v_add_f32_dpp v112, v104, v104 row_half_mirror row_mask:0xf bank_mask:0x5 bound_ctrl:1
	v_add_f32_dpp v112, v108, v108 row_half_mirror row_mask:0xf bank_mask:0xa bound_ctrl:1
	v_add_f32_dpp v113, v105, v105 row_half_mirror row_mask:0xf bank_mask:0x5 bound_ctrl:1
	v_add_f32_dpp v113, v109, v109 row_half_mirror row_mask:0xf bank_mask:0xa bound_ctrl:1
	s_mov_b32 vcc_lo, 0xcccccccc
	s_mov_b32 vcc_hi, 0xcccccccc
	v_cndmask_b32 v116, v112, v110, vcc
	v_cndmask_b32 v117, v113, v111, vcc
	v_cndmask_b32 v114, v110, v112, vcc
	v_cndmask_b32 v115, v111, v113, vcc
	v_add_f32_dpp v114, v116, v114 quad_perm:[2,3,0,1] row_mask:0xf bank_mask:0xf bound_ctrl:1
	v_add_f32_dpp v115, v117, v115 quad_perm:[2,3,0,1] row_mask:0xf bank_mask:0xf bound_ctrl:1
	s_mov_b32 vcc_lo, 0xaaaaaaaa
	s_mov_b32 vcc_hi, 0xaaaaaaaa
	v_cndmask_b32 v116, v115, v114, vcc
	v_cndmask_b32 v117, v114, v115, vcc
	s_nop 0
	v_add_f32_dpp v18, v116, v117 quad_perm:[1,0,3,2] row_mask:0xf bank_mask:0xf bound_ctrl:1
	ds_read_b128 v[234:237], v5 offset:29440
	ds_read_b128 v[238:241], v5 offset:29696
	ds_read_b128 v[242:245], v5 offset:29952
	ds_read_b128 v[246:249], v5 offset:30208
	ds_read_b32 v250, v9 offset:29184
	ds_read_b128 v[164:167], v5 offset:30720
	v_add_f32_dpp v146, v146, v146 quad_perm:[1,0,3,2] row_mask:0xf bank_mask:0xf bound_ctrl:1
	v_pk_mul_f32 v[180:181], v[138:139], v[180:181]
	v_pk_fma_f32 v[180:181], v[140:141], v[182:183], v[180:181]
	v_add_f32_dpp v146, v146, v146 quad_perm:[2,3,0,1] row_mask:0xf bank_mask:0xf bound_ctrl:1
	s_waitcnt lgkmcnt(12)
	v_pk_mul_f32 v[198:199], v[198:199], v[206:207] op_sel_hi:[1,0]
	v_add_f32_dpp v146, v146, v146 row_half_mirror row_mask:0xf bank_mask:0xf bound_ctrl:1
	v_pk_mul_f32 v[200:201], v[200:201], v[206:207] op_sel_hi:[1,0]
	v_add_f32 v148, v180, v181
	v_add_f32_dpp v146, v146, v146 row_mirror row_mask:0xf bank_mask:0xf bound_ctrl:1
	v_pk_fma_f32 v[198:199], v[146:147], v[190:191], v[198:199] op_sel_hi:[0,1,1] neg_lo:[1,0,0] neg_hi:[1,0,0]
	v_pk_fma_f32 v[200:201], v[146:147], v[192:193], v[200:201] op_sel_hi:[0,1,1] neg_lo:[1,0,0] neg_hi:[1,0,0]
	v_pk_fma_f32 v[138:139], v[138:139], v[194:195], v[198:199]
	v_pk_fma_f32 v[140:141], v[140:141], v[196:197], v[200:201]
	v_pk_mul_f32 v[144:145], v[138:139], v[208:209]
	v_pk_fma_f32 v[144:145], v[140:141], v[210:211], v[144:145]
	v_add_f32 v146, v144, v145
	ds_read_b128 v[168:171], v5 offset:30976
	ds_read_b128 v[172:175], v5 offset:31232
	ds_read_b128 v[176:179], v5 offset:31488
	ds_read_b128 v[180:183], v5 offset:31744
	ds_read_b32 v184, v9 offset:30720
	ds_read_b128 v[186:189], v5 offset:32256
	v_add_f32_dpp v146, v146, v146 quad_perm:[1,0,3,2] row_mask:0xf bank_mask:0xf bound_ctrl:1
	v_pk_mul_f32 v[202:203], v[138:139], v[202:203]
	v_pk_fma_f32 v[202:203], v[140:141], v[204:205], v[202:203]
	v_add_f32_dpp v146, v146, v146 quad_perm:[2,3,0,1] row_mask:0xf bank_mask:0xf bound_ctrl:1
	s_waitcnt lgkmcnt(12)
	v_pk_mul_f32 v[220:221], v[220:221], v[228:229] op_sel_hi:[1,0]
	v_add_f32_dpp v146, v146, v146 row_half_mirror row_mask:0xf bank_mask:0xf bound_ctrl:1
	v_pk_mul_f32 v[222:223], v[222:223], v[228:229] op_sel_hi:[1,0]
	v_add_f32 v149, v202, v203
	v_add_f32_dpp v146, v146, v146 row_mirror row_mask:0xf bank_mask:0xf bound_ctrl:1
	v_pk_fma_f32 v[220:221], v[146:147], v[212:213], v[220:221] op_sel_hi:[0,1,1] neg_lo:[1,0,0] neg_hi:[1,0,0]
	v_pk_fma_f32 v[222:223], v[146:147], v[214:215], v[222:223] op_sel_hi:[0,1,1] neg_lo:[1,0,0] neg_hi:[1,0,0]
	v_pk_fma_f32 v[138:139], v[138:139], v[216:217], v[220:221]
	v_pk_fma_f32 v[140:141], v[140:141], v[218:219], v[222:223]
	v_pk_mul_f32 v[144:145], v[138:139], v[230:231]
	v_pk_fma_f32 v[144:145], v[140:141], v[232:233], v[144:145]
	v_add_f32 v146, v144, v145
	ds_read_b128 v[190:193], v5 offset:32512
	ds_read_b128 v[194:197], v5 offset:32768
	ds_read_b128 v[198:201], v5 offset:33024
	ds_read_b128 v[202:205], v5 offset:33280
	ds_read_b32 v206, v9 offset:32256
	ds_read_b128 v[208:211], v5 offset:33792
	v_add_f32_dpp v146, v146, v146 quad_perm:[1,0,3,2] row_mask:0xf bank_mask:0xf bound_ctrl:1
	v_pk_mul_f32 v[224:225], v[138:139], v[224:225]
	v_pk_fma_f32 v[224:225], v[140:141], v[226:227], v[224:225]
	v_add_f32_dpp v146, v146, v146 quad_perm:[2,3,0,1] row_mask:0xf bank_mask:0xf bound_ctrl:1
	s_waitcnt lgkmcnt(12)
	v_pk_mul_f32 v[242:243], v[242:243], v[250:251] op_sel_hi:[1,0]
	v_add_f32_dpp v146, v146, v146 row_half_mirror row_mask:0xf bank_mask:0xf bound_ctrl:1
	v_pk_mul_f32 v[244:245], v[244:245], v[250:251] op_sel_hi:[1,0]
	v_add_f32 v150, v224, v225
	v_add_f32_dpp v146, v146, v146 row_mirror row_mask:0xf bank_mask:0xf bound_ctrl:1
	v_pk_fma_f32 v[242:243], v[146:147], v[234:235], v[242:243] op_sel_hi:[0,1,1] neg_lo:[1,0,0] neg_hi:[1,0,0]
	v_pk_fma_f32 v[244:245], v[146:147], v[236:237], v[244:245] op_sel_hi:[0,1,1] neg_lo:[1,0,0] neg_hi:[1,0,0]
	v_pk_fma_f32 v[138:139], v[138:139], v[238:239], v[242:243]
	v_pk_fma_f32 v[140:141], v[140:141], v[240:241], v[244:245]
	v_pk_mul_f32 v[144:145], v[138:139], v[164:165]
	v_pk_fma_f32 v[144:145], v[140:141], v[166:167], v[144:145]
	v_add_f32 v146, v144, v145
	ds_read_b128 v[212:215], v5 offset:34048
	ds_read_b128 v[216:219], v5 offset:34304
	ds_read_b128 v[220:223], v5 offset:34560
	ds_read_b128 v[224:227], v5 offset:34816
	ds_read_b32 v228, v9 offset:33792
	ds_read_b128 v[230:233], v5 offset:35328
	v_add_f32_dpp v146, v146, v146 quad_perm:[1,0,3,2] row_mask:0xf bank_mask:0xf bound_ctrl:1
	v_pk_mul_f32 v[246:247], v[138:139], v[246:247]
	v_pk_fma_f32 v[246:247], v[140:141], v[248:249], v[246:247]
	v_add_f32_dpp v146, v146, v146 quad_perm:[2,3,0,1] row_mask:0xf bank_mask:0xf bound_ctrl:1
	s_waitcnt lgkmcnt(12)
	v_pk_mul_f32 v[176:177], v[176:177], v[184:185] op_sel_hi:[1,0]
	v_add_f32_dpp v146, v146, v146 row_half_mirror row_mask:0xf bank_mask:0xf bound_ctrl:1
	v_pk_mul_f32 v[178:179], v[178:179], v[184:185] op_sel_hi:[1,0]
	v_add_f32 v151, v246, v247
	v_add_f32_dpp v146, v146, v146 row_mirror row_mask:0xf bank_mask:0xf bound_ctrl:1
	v_pk_fma_f32 v[176:177], v[146:147], v[168:169], v[176:177] op_sel_hi:[0,1,1] neg_lo:[1,0,0] neg_hi:[1,0,0]
	v_pk_fma_f32 v[178:179], v[146:147], v[170:171], v[178:179] op_sel_hi:[0,1,1] neg_lo:[1,0,0] neg_hi:[1,0,0]
	v_pk_fma_f32 v[138:139], v[138:139], v[172:173], v[176:177]
	v_pk_fma_f32 v[140:141], v[140:141], v[174:175], v[178:179]
	v_pk_mul_f32 v[144:145], v[138:139], v[186:187]
	v_pk_fma_f32 v[144:145], v[140:141], v[188:189], v[144:145]
	v_add_f32 v146, v144, v145
	ds_read_b128 v[234:237], v5 offset:35584
	ds_read_b128 v[238:241], v5 offset:35840
	ds_read_b128 v[242:245], v5 offset:36096
	ds_read_b128 v[246:249], v5 offset:36352
	ds_read_b32 v250, v9 offset:35328
	ds_read_b128 v[164:167], v5 offset:36864
	v_add_f32_dpp v146, v146, v146 quad_perm:[1,0,3,2] row_mask:0xf bank_mask:0xf bound_ctrl:1
	v_pk_mul_f32 v[180:181], v[138:139], v[180:181]
	v_pk_fma_f32 v[180:181], v[140:141], v[182:183], v[180:181]
	v_add_f32_dpp v146, v146, v146 quad_perm:[2,3,0,1] row_mask:0xf bank_mask:0xf bound_ctrl:1
	s_waitcnt lgkmcnt(12)
	v_pk_mul_f32 v[198:199], v[198:199], v[206:207] op_sel_hi:[1,0]
	v_add_f32_dpp v146, v146, v146 row_half_mirror row_mask:0xf bank_mask:0xf bound_ctrl:1
	v_pk_mul_f32 v[200:201], v[200:201], v[206:207] op_sel_hi:[1,0]
	v_add_f32 v152, v180, v181
	v_add_f32_dpp v146, v146, v146 row_mirror row_mask:0xf bank_mask:0xf bound_ctrl:1
	v_pk_fma_f32 v[198:199], v[146:147], v[190:191], v[198:199] op_sel_hi:[0,1,1] neg_lo:[1,0,0] neg_hi:[1,0,0]
	v_pk_fma_f32 v[200:201], v[146:147], v[192:193], v[200:201] op_sel_hi:[0,1,1] neg_lo:[1,0,0] neg_hi:[1,0,0]
	v_pk_fma_f32 v[138:139], v[138:139], v[194:195], v[198:199]
	v_pk_fma_f32 v[140:141], v[140:141], v[196:197], v[200:201]
	v_pk_mul_f32 v[144:145], v[138:139], v[208:209]
	v_pk_fma_f32 v[144:145], v[140:141], v[210:211], v[144:145]
	v_add_f32 v146, v144, v145
	ds_read_b128 v[168:171], v5 offset:37120
	ds_read_b128 v[172:175], v5 offset:37376
	ds_read_b128 v[176:179], v5 offset:37632
	ds_read_b128 v[180:183], v5 offset:37888
	ds_read_b32 v184, v9 offset:36864
	ds_read_b128 v[186:189], v5 offset:38400
	v_add_f32_dpp v146, v146, v146 quad_perm:[1,0,3,2] row_mask:0xf bank_mask:0xf bound_ctrl:1
	v_pk_mul_f32 v[202:203], v[138:139], v[202:203]
	v_pk_fma_f32 v[202:203], v[140:141], v[204:205], v[202:203]
	v_add_f32_dpp v146, v146, v146 quad_perm:[2,3,0,1] row_mask:0xf bank_mask:0xf bound_ctrl:1
	s_waitcnt lgkmcnt(12)
	v_pk_mul_f32 v[220:221], v[220:221], v[228:229] op_sel_hi:[1,0]
	v_add_f32_dpp v146, v146, v146 row_half_mirror row_mask:0xf bank_mask:0xf bound_ctrl:1
	v_pk_mul_f32 v[222:223], v[222:223], v[228:229] op_sel_hi:[1,0]
	v_add_f32 v153, v202, v203
	v_add_f32_dpp v146, v146, v146 row_mirror row_mask:0xf bank_mask:0xf bound_ctrl:1
	v_pk_fma_f32 v[220:221], v[146:147], v[212:213], v[220:221] op_sel_hi:[0,1,1] neg_lo:[1,0,0] neg_hi:[1,0,0]
	v_pk_fma_f32 v[222:223], v[146:147], v[214:215], v[222:223] op_sel_hi:[0,1,1] neg_lo:[1,0,0] neg_hi:[1,0,0]
	v_pk_fma_f32 v[138:139], v[138:139], v[216:217], v[220:221]
	v_pk_fma_f32 v[140:141], v[140:141], v[218:219], v[222:223]
	v_pk_mul_f32 v[144:145], v[138:139], v[230:231]
	v_pk_fma_f32 v[144:145], v[140:141], v[232:233], v[144:145]
	v_add_f32 v146, v144, v145
	ds_read_b128 v[190:193], v5 offset:38656
	ds_read_b128 v[194:197], v5 offset:38912
	ds_read_b128 v[198:201], v5 offset:39168
	ds_read_b128 v[202:205], v5 offset:39424
	ds_read_b32 v206, v9 offset:38400
	ds_read_b128 v[208:211], v5 offset:39936
	v_add_f32_dpp v146, v146, v146 quad_perm:[1,0,3,2] row_mask:0xf bank_mask:0xf bound_ctrl:1
	v_pk_mul_f32 v[224:225], v[138:139], v[224:225]
	v_pk_fma_f32 v[224:225], v[140:141], v[226:227], v[224:225]
	v_add_f32_dpp v146, v146, v146 quad_perm:[2,3,0,1] row_mask:0xf bank_mask:0xf bound_ctrl:1
	s_waitcnt lgkmcnt(12)
	v_pk_mul_f32 v[242:243], v[242:243], v[250:251] op_sel_hi:[1,0]
	v_add_f32_dpp v146, v146, v146 row_half_mirror row_mask:0xf bank_mask:0xf bound_ctrl:1
	v_pk_mul_f32 v[244:245], v[244:245], v[250:251] op_sel_hi:[1,0]
	v_add_f32 v154, v224, v225
	v_add_f32_dpp v146, v146, v146 row_mirror row_mask:0xf bank_mask:0xf bound_ctrl:1
	v_pk_fma_f32 v[242:243], v[146:147], v[234:235], v[242:243] op_sel_hi:[0,1,1] neg_lo:[1,0,0] neg_hi:[1,0,0]
	v_pk_fma_f32 v[244:245], v[146:147], v[236:237], v[244:245] op_sel_hi:[0,1,1] neg_lo:[1,0,0] neg_hi:[1,0,0]
	v_pk_fma_f32 v[138:139], v[138:139], v[238:239], v[242:243]
	v_pk_fma_f32 v[140:141], v[140:141], v[240:241], v[244:245]
	v_pk_mul_f32 v[144:145], v[138:139], v[164:165]
	v_pk_fma_f32 v[144:145], v[140:141], v[166:167], v[144:145]
	v_add_f32 v146, v144, v145
	ds_read_b128 v[212:215], v5 offset:40192
	ds_read_b128 v[216:219], v5 offset:40448
	ds_read_b128 v[220:223], v5 offset:40704
	ds_read_b128 v[224:227], v5 offset:40960
	ds_read_b32 v228, v9 offset:39936
	ds_read_b128 v[230:233], v5 offset:41472
	v_add_f32_dpp v146, v146, v146 quad_perm:[1,0,3,2] row_mask:0xf bank_mask:0xf bound_ctrl:1
	v_pk_mul_f32 v[246:247], v[138:139], v[246:247]
	v_pk_fma_f32 v[246:247], v[140:141], v[248:249], v[246:247]
	v_add_f32_dpp v146, v146, v146 quad_perm:[2,3,0,1] row_mask:0xf bank_mask:0xf bound_ctrl:1
	s_waitcnt lgkmcnt(12)
	v_pk_mul_f32 v[176:177], v[176:177], v[184:185] op_sel_hi:[1,0]
	v_add_f32_dpp v146, v146, v146 row_half_mirror row_mask:0xf bank_mask:0xf bound_ctrl:1
	v_pk_mul_f32 v[178:179], v[178:179], v[184:185] op_sel_hi:[1,0]
	v_add_f32 v155, v246, v247
	v_add_f32_dpp v146, v146, v146 row_mirror row_mask:0xf bank_mask:0xf bound_ctrl:1
	v_pk_fma_f32 v[176:177], v[146:147], v[168:169], v[176:177] op_sel_hi:[0,1,1] neg_lo:[1,0,0] neg_hi:[1,0,0]
	v_pk_fma_f32 v[178:179], v[146:147], v[170:171], v[178:179] op_sel_hi:[0,1,1] neg_lo:[1,0,0] neg_hi:[1,0,0]
	v_pk_fma_f32 v[138:139], v[138:139], v[172:173], v[176:177]
	v_pk_fma_f32 v[140:141], v[140:141], v[174:175], v[178:179]
	v_pk_mul_f32 v[144:145], v[138:139], v[186:187]
	v_pk_fma_f32 v[144:145], v[140:141], v[188:189], v[144:145]
	v_add_f32 v146, v144, v145
	ds_read_b128 v[234:237], v5 offset:41728
	ds_read_b128 v[238:241], v5 offset:41984
	ds_read_b128 v[242:245], v5 offset:42240
	ds_read_b128 v[246:249], v5 offset:42496
	ds_read_b32 v250, v9 offset:41472
	ds_read_b128 v[164:167], v5 offset:43008
	v_add_f32_dpp v146, v146, v146 quad_perm:[1,0,3,2] row_mask:0xf bank_mask:0xf bound_ctrl:1
	v_pk_mul_f32 v[180:181], v[138:139], v[180:181]
	v_pk_fma_f32 v[180:181], v[140:141], v[182:183], v[180:181]
	v_add_f32_dpp v146, v146, v146 quad_perm:[2,3,0,1] row_mask:0xf bank_mask:0xf bound_ctrl:1
	s_waitcnt lgkmcnt(12)
	v_pk_mul_f32 v[198:199], v[198:199], v[206:207] op_sel_hi:[1,0]
	v_add_f32_dpp v146, v146, v146 row_half_mirror row_mask:0xf bank_mask:0xf bound_ctrl:1
	v_pk_mul_f32 v[200:201], v[200:201], v[206:207] op_sel_hi:[1,0]
	v_add_f32 v156, v180, v181
	v_add_f32_dpp v146, v146, v146 row_mirror row_mask:0xf bank_mask:0xf bound_ctrl:1
	v_pk_fma_f32 v[198:199], v[146:147], v[190:191], v[198:199] op_sel_hi:[0,1,1] neg_lo:[1,0,0] neg_hi:[1,0,0]
	v_pk_fma_f32 v[200:201], v[146:147], v[192:193], v[200:201] op_sel_hi:[0,1,1] neg_lo:[1,0,0] neg_hi:[1,0,0]
	v_pk_fma_f32 v[138:139], v[138:139], v[194:195], v[198:199]
	v_pk_fma_f32 v[140:141], v[140:141], v[196:197], v[200:201]
	v_pk_mul_f32 v[144:145], v[138:139], v[208:209]
	v_pk_fma_f32 v[144:145], v[140:141], v[210:211], v[144:145]
	v_add_f32 v146, v144, v145
	ds_read_b128 v[168:171], v5 offset:43264
	ds_read_b128 v[172:175], v5 offset:43520
	ds_read_b128 v[176:179], v5 offset:43776
	ds_read_b128 v[180:183], v5 offset:44032
	ds_read_b32 v184, v9 offset:43008
	ds_read_b128 v[186:189], v5 offset:44544
	v_add_f32_dpp v146, v146, v146 quad_perm:[1,0,3,2] row_mask:0xf bank_mask:0xf bound_ctrl:1
	v_pk_mul_f32 v[202:203], v[138:139], v[202:203]
	v_pk_fma_f32 v[202:203], v[140:141], v[204:205], v[202:203]
	v_add_f32_dpp v146, v146, v146 quad_perm:[2,3,0,1] row_mask:0xf bank_mask:0xf bound_ctrl:1
	s_waitcnt lgkmcnt(12)
	v_pk_mul_f32 v[220:221], v[220:221], v[228:229] op_sel_hi:[1,0]
	v_add_f32_dpp v146, v146, v146 row_half_mirror row_mask:0xf bank_mask:0xf bound_ctrl:1
	v_pk_mul_f32 v[222:223], v[222:223], v[228:229] op_sel_hi:[1,0]
	v_add_f32 v157, v202, v203
	v_add_f32_dpp v146, v146, v146 row_mirror row_mask:0xf bank_mask:0xf bound_ctrl:1
	v_pk_fma_f32 v[220:221], v[146:147], v[212:213], v[220:221] op_sel_hi:[0,1,1] neg_lo:[1,0,0] neg_hi:[1,0,0]
	v_pk_fma_f32 v[222:223], v[146:147], v[214:215], v[222:223] op_sel_hi:[0,1,1] neg_lo:[1,0,0] neg_hi:[1,0,0]
	v_pk_fma_f32 v[138:139], v[138:139], v[216:217], v[220:221]
	v_pk_fma_f32 v[140:141], v[140:141], v[218:219], v[222:223]
	v_pk_mul_f32 v[144:145], v[138:139], v[230:231]
	v_pk_fma_f32 v[144:145], v[140:141], v[232:233], v[144:145]
	v_add_f32 v146, v144, v145
	ds_read_b128 v[190:193], v5 offset:44800
	ds_read_b128 v[194:197], v5 offset:45056
	ds_read_b128 v[198:201], v5 offset:45312
	ds_read_b128 v[202:205], v5 offset:45568
	ds_read_b32 v206, v9 offset:44544
	ds_read_b128 v[208:211], v5 offset:46080
	v_add_f32_dpp v146, v146, v146 quad_perm:[1,0,3,2] row_mask:0xf bank_mask:0xf bound_ctrl:1
	v_pk_mul_f32 v[224:225], v[138:139], v[224:225]
	v_pk_fma_f32 v[224:225], v[140:141], v[226:227], v[224:225]
	v_add_f32_dpp v146, v146, v146 quad_perm:[2,3,0,1] row_mask:0xf bank_mask:0xf bound_ctrl:1
	s_waitcnt lgkmcnt(12)
	v_pk_mul_f32 v[242:243], v[242:243], v[250:251] op_sel_hi:[1,0]
	v_add_f32_dpp v146, v146, v146 row_half_mirror row_mask:0xf bank_mask:0xf bound_ctrl:1
	v_pk_mul_f32 v[244:245], v[244:245], v[250:251] op_sel_hi:[1,0]
	v_add_f32 v158, v224, v225
	v_add_f32_dpp v146, v146, v146 row_mirror row_mask:0xf bank_mask:0xf bound_ctrl:1
	v_pk_fma_f32 v[242:243], v[146:147], v[234:235], v[242:243] op_sel_hi:[0,1,1] neg_lo:[1,0,0] neg_hi:[1,0,0]
	v_pk_fma_f32 v[244:245], v[146:147], v[236:237], v[244:245] op_sel_hi:[0,1,1] neg_lo:[1,0,0] neg_hi:[1,0,0]
	v_pk_fma_f32 v[138:139], v[138:139], v[238:239], v[242:243]
	v_pk_fma_f32 v[140:141], v[140:141], v[240:241], v[244:245]
	v_pk_mul_f32 v[144:145], v[138:139], v[164:165]
	v_pk_fma_f32 v[144:145], v[140:141], v[166:167], v[144:145]
	v_add_f32 v146, v144, v145
	ds_read_b128 v[212:215], v5 offset:46336
	ds_read_b128 v[216:219], v5 offset:46592
	ds_read_b128 v[220:223], v5 offset:46848
	ds_read_b128 v[224:227], v5 offset:47104
	ds_read_b32 v228, v9 offset:46080
	ds_read_b128 v[230:233], v5 offset:47616
	v_add_f32_dpp v146, v146, v146 quad_perm:[1,0,3,2] row_mask:0xf bank_mask:0xf bound_ctrl:1
	v_pk_mul_f32 v[246:247], v[138:139], v[246:247]
	v_pk_fma_f32 v[246:247], v[140:141], v[248:249], v[246:247]
	v_add_f32_dpp v146, v146, v146 quad_perm:[2,3,0,1] row_mask:0xf bank_mask:0xf bound_ctrl:1
	s_waitcnt lgkmcnt(12)
	v_pk_mul_f32 v[176:177], v[176:177], v[184:185] op_sel_hi:[1,0]
	v_add_f32_dpp v146, v146, v146 row_half_mirror row_mask:0xf bank_mask:0xf bound_ctrl:1
	v_pk_mul_f32 v[178:179], v[178:179], v[184:185] op_sel_hi:[1,0]
	v_add_f32 v159, v246, v247
	v_add_f32_dpp v146, v146, v146 row_mirror row_mask:0xf bank_mask:0xf bound_ctrl:1
	v_pk_fma_f32 v[176:177], v[146:147], v[168:169], v[176:177] op_sel_hi:[0,1,1] neg_lo:[1,0,0] neg_hi:[1,0,0]
	v_pk_fma_f32 v[178:179], v[146:147], v[170:171], v[178:179] op_sel_hi:[0,1,1] neg_lo:[1,0,0] neg_hi:[1,0,0]
	v_pk_fma_f32 v[138:139], v[138:139], v[172:173], v[176:177]
	v_pk_fma_f32 v[140:141], v[140:141], v[174:175], v[178:179]
	v_pk_mul_f32 v[144:145], v[138:139], v[186:187]
	v_pk_fma_f32 v[144:145], v[140:141], v[188:189], v[144:145]
	v_add_f32 v146, v144, v145
	ds_read_b128 v[234:237], v5 offset:47872
	ds_read_b128 v[238:241], v5 offset:48128
	ds_read_b128 v[242:245], v5 offset:48384
	ds_read_b128 v[246:249], v5 offset:48640
	ds_read_b32 v250, v9 offset:47616
	v_add_f32_dpp v146, v146, v146 quad_perm:[1,0,3,2] row_mask:0xf bank_mask:0xf bound_ctrl:1
	v_pk_mul_f32 v[180:181], v[138:139], v[180:181]
	v_pk_fma_f32 v[180:181], v[140:141], v[182:183], v[180:181]
	v_add_f32_dpp v146, v146, v146 quad_perm:[2,3,0,1] row_mask:0xf bank_mask:0xf bound_ctrl:1
	s_waitcnt lgkmcnt(11)
	v_pk_mul_f32 v[198:199], v[198:199], v[206:207] op_sel_hi:[1,0]
	v_add_f32_dpp v146, v146, v146 row_half_mirror row_mask:0xf bank_mask:0xf bound_ctrl:1
	v_pk_mul_f32 v[200:201], v[200:201], v[206:207] op_sel_hi:[1,0]
	v_add_f32 v160, v180, v181
	v_add_f32_dpp v146, v146, v146 row_mirror row_mask:0xf bank_mask:0xf bound_ctrl:1
	v_pk_fma_f32 v[198:199], v[146:147], v[190:191], v[198:199] op_sel_hi:[0,1,1] neg_lo:[1,0,0] neg_hi:[1,0,0]
	v_pk_fma_f32 v[200:201], v[146:147], v[192:193], v[200:201] op_sel_hi:[0,1,1] neg_lo:[1,0,0] neg_hi:[1,0,0]
	v_pk_fma_f32 v[138:139], v[138:139], v[194:195], v[198:199]
	v_pk_fma_f32 v[140:141], v[140:141], v[196:197], v[200:201]
	v_pk_mul_f32 v[144:145], v[138:139], v[208:209]
	v_pk_fma_f32 v[144:145], v[140:141], v[210:211], v[144:145]
	v_add_f32 v146, v144, v145
	s_nop 1
	v_add_f32_dpp v146, v146, v146 quad_perm:[1,0,3,2] row_mask:0xf bank_mask:0xf bound_ctrl:1
	v_pk_mul_f32 v[202:203], v[138:139], v[202:203]
	v_pk_fma_f32 v[202:203], v[140:141], v[204:205], v[202:203]
	v_add_f32_dpp v146, v146, v146 quad_perm:[2,3,0,1] row_mask:0xf bank_mask:0xf bound_ctrl:1
	s_waitcnt lgkmcnt(5)
	v_pk_mul_f32 v[220:221], v[220:221], v[228:229] op_sel_hi:[1,0]
	v_add_f32_dpp v146, v146, v146 row_half_mirror row_mask:0xf bank_mask:0xf bound_ctrl:1
	v_pk_mul_f32 v[222:223], v[222:223], v[228:229] op_sel_hi:[1,0]
	v_add_f32 v161, v202, v203
	v_add_f32_dpp v146, v146, v146 row_mirror row_mask:0xf bank_mask:0xf bound_ctrl:1
	v_pk_fma_f32 v[220:221], v[146:147], v[212:213], v[220:221] op_sel_hi:[0,1,1] neg_lo:[1,0,0] neg_hi:[1,0,0]
	v_pk_fma_f32 v[222:223], v[146:147], v[214:215], v[222:223] op_sel_hi:[0,1,1] neg_lo:[1,0,0] neg_hi:[1,0,0]
	v_pk_fma_f32 v[138:139], v[138:139], v[216:217], v[220:221]
	v_pk_fma_f32 v[140:141], v[140:141], v[218:219], v[222:223]
	v_pk_mul_f32 v[144:145], v[138:139], v[230:231]
	v_pk_fma_f32 v[144:145], v[140:141], v[232:233], v[144:145]
	v_add_f32 v146, v144, v145
	s_nop 1
	v_add_f32_dpp v146, v146, v146 quad_perm:[1,0,3,2] row_mask:0xf bank_mask:0xf bound_ctrl:1
	v_pk_mul_f32 v[224:225], v[138:139], v[224:225]
	v_pk_fma_f32 v[224:225], v[140:141], v[226:227], v[224:225]
	v_add_f32_dpp v146, v146, v146 quad_perm:[2,3,0,1] row_mask:0xf bank_mask:0xf bound_ctrl:1
	s_waitcnt lgkmcnt(0)
	v_pk_mul_f32 v[242:243], v[242:243], v[250:251] op_sel_hi:[1,0]
	v_add_f32_dpp v146, v146, v146 row_half_mirror row_mask:0xf bank_mask:0xf bound_ctrl:1
	v_pk_mul_f32 v[244:245], v[244:245], v[250:251] op_sel_hi:[1,0]
	v_add_f32 v162, v224, v225
	v_add_f32_dpp v146, v146, v146 row_mirror row_mask:0xf bank_mask:0xf bound_ctrl:1
	v_pk_fma_f32 v[242:243], v[146:147], v[234:235], v[242:243] op_sel_hi:[0,1,1] neg_lo:[1,0,0] neg_hi:[1,0,0]
	v_pk_fma_f32 v[244:245], v[146:147], v[236:237], v[244:245] op_sel_hi:[0,1,1] neg_lo:[1,0,0] neg_hi:[1,0,0]
	v_pk_fma_f32 v[138:139], v[138:139], v[238:239], v[242:243]
	v_pk_fma_f32 v[140:141], v[140:141], v[240:241], v[244:245]
	v_pk_mul_f32 v[246:247], v[138:139], v[246:247]
	v_pk_fma_f32 v[246:247], v[140:141], v[248:249], v[246:247]
	v_add_f32 v163, v246, v247
	s_nop 0
	v_add_f32_dpp v102, v148, v148 row_mirror row_mask:0xf bank_mask:0x3 bound_ctrl:1
	v_add_f32_dpp v102, v156, v156 row_mirror row_mask:0xf bank_mask:0xc bound_ctrl:1
	v_add_f32_dpp v103, v149, v149 row_mirror row_mask:0xf bank_mask:0x3 bound_ctrl:1
	v_add_f32_dpp v103, v157, v157 row_mirror row_mask:0xf bank_mask:0xc bound_ctrl:1
	v_add_f32_dpp v104, v150, v150 row_mirror row_mask:0xf bank_mask:0x3 bound_ctrl:1
	v_add_f32_dpp v104, v158, v158 row_mirror row_mask:0xf bank_mask:0xc bound_ctrl:1
	v_add_f32_dpp v105, v151, v151 row_mirror row_mask:0xf bank_mask:0x3 bound_ctrl:1
	v_add_f32_dpp v105, v159, v159 row_mirror row_mask:0xf bank_mask:0xc bound_ctrl:1
	v_add_f32_dpp v106, v152, v152 row_mirror row_mask:0xf bank_mask:0x3 bound_ctrl:1
	v_add_f32_dpp v106, v160, v160 row_mirror row_mask:0xf bank_mask:0xc bound_ctrl:1
	v_add_f32_dpp v107, v153, v153 row_mirror row_mask:0xf bank_mask:0x3 bound_ctrl:1
	v_add_f32_dpp v107, v161, v161 row_mirror row_mask:0xf bank_mask:0xc bound_ctrl:1
	v_add_f32_dpp v108, v154, v154 row_mirror row_mask:0xf bank_mask:0x3 bound_ctrl:1
	v_add_f32_dpp v108, v162, v162 row_mirror row_mask:0xf bank_mask:0xc bound_ctrl:1
	v_add_f32_dpp v109, v155, v155 row_mirror row_mask:0xf bank_mask:0x3 bound_ctrl:1
	v_add_f32_dpp v109, v163, v163 row_mirror row_mask:0xf bank_mask:0xc bound_ctrl:1
	v_add_f32_dpp v110, v102, v102 row_half_mirror row_mask:0xf bank_mask:0x5 bound_ctrl:1
	v_add_f32_dpp v110, v106, v106 row_half_mirror row_mask:0xf bank_mask:0xa bound_ctrl:1
	v_add_f32_dpp v111, v103, v103 row_half_mirror row_mask:0xf bank_mask:0x5 bound_ctrl:1
	v_add_f32_dpp v111, v107, v107 row_half_mirror row_mask:0xf bank_mask:0xa bound_ctrl:1
	v_add_f32_dpp v112, v104, v104 row_half_mirror row_mask:0xf bank_mask:0x5 bound_ctrl:1
	v_add_f32_dpp v112, v108, v108 row_half_mirror row_mask:0xf bank_mask:0xa bound_ctrl:1
	v_add_f32_dpp v113, v105, v105 row_half_mirror row_mask:0xf bank_mask:0x5 bound_ctrl:1
	v_add_f32_dpp v113, v109, v109 row_half_mirror row_mask:0xf bank_mask:0xa bound_ctrl:1
	s_mov_b32 vcc_lo, 0xcccccccc
	s_mov_b32 vcc_hi, 0xcccccccc
	v_cndmask_b32 v116, v112, v110, vcc
	v_cndmask_b32 v117, v113, v111, vcc
	v_cndmask_b32 v114, v110, v112, vcc
	v_cndmask_b32 v115, v111, v113, vcc
	v_add_f32_dpp v114, v116, v114 quad_perm:[2,3,0,1] row_mask:0xf bank_mask:0xf bound_ctrl:1
	v_add_f32_dpp v115, v117, v115 quad_perm:[2,3,0,1] row_mask:0xf bank_mask:0xf bound_ctrl:1
	s_mov_b32 vcc_lo, 0xaaaaaaaa
	s_mov_b32 vcc_hi, 0xaaaaaaaa
	v_cndmask_b32 v116, v115, v114, vcc
	v_cndmask_b32 v117, v114, v115, vcc
	s_nop 0
	v_add_f32_dpp v19, v116, v117 quad_perm:[1,0,3,2] row_mask:0xf bank_mask:0xf bound_ctrl:1

; #define SCAN_BAR() asm volatile("s_barrier" ::: "memory")
; __device__ __forceinline__ void scan_unit(const Ctx& C0, const float* scn, int T, int quarter, const float* S0, float* Sout, unsigned char* obase, int mode) {
;     ...
;             if (mode == 0) { *(float*)(obase + (size_t)(k * 32 + q) * UPITCH_B + rl * 4) = osel0; *(float*)(obase + (size_t)(k * 32 + 16 + q) * UPITCH_B + rl * 4) = osel1; }
;             SCAN_BAR();
	v_lshl_add_u64 v[14:15], v[6:7], 0, s[0:1]
	v_add_co_u32_e32 v16, vcc, 0xfc29000, v14
	s_mov_b32 s8, 0xfc7f000
	s_nop 0
	v_addc_co_u32_e32 v17, vcc, 0, v15, vcc
	global_store_dword v[16:17], v18, off offset:768
	v_add_co_u32_e32 v16, vcc, 0xfc54000, v14
	s_add_u32 s0, s0, 0xac000
	s_nop 0
	v_addc_co_u32_e32 v17, vcc, 0, v15, vcc
	global_store_dword v[16:17], v19, off offset:768
	s_barrier
	ds_read_b128 v[164:167], v10 offset:0
	ds_read_b128 v[168:171], v10 offset:256
	ds_read_b128 v[172:175], v10 offset:512
	ds_read_b128 v[176:179], v10 offset:768
	ds_read_b128 v[180:183], v10 offset:1024
	ds_read_b32 v184, v11 offset:0
	ds_read_b128 v[186:189], v10 offset:1536
	ds_read_b128 v[190:193], v10 offset:1792
	ds_read_b128 v[194:197], v10 offset:2048
	ds_read_b128 v[198:201], v10 offset:2304
	ds_read_b128 v[202:205], v10 offset:2560
	ds_read_b32 v206, v11 offset:1536
	ds_read_b128 v[208:211], v10 offset:3072
	s_waitcnt lgkmcnt(12)
	v_pk_mul_f32 v[144:145], v[138:139], v[164:165]
	v_pk_fma_f32 v[144:145], v[140:141], v[166:167], v[144:145]
	v_add_f32 v146, v144, v145
	ds_read_b128 v[212:215], v10 offset:3328
	ds_read_b128 v[216:219], v10 offset:3584
	ds_read_b128 v[220:223], v10 offset:3840
	ds_read_b128 v[224:227], v10 offset:4096
	ds_read_b32 v228, v11 offset:3072
	ds_read_b128 v[230:233], v10 offset:4608
	v_add_f32_dpp v146, v146, v146 quad_perm:[1,0,3,2] row_mask:0xf bank_mask:0xf bound_ctrl:1
	s_nop 0
	s_nop 0
	v_add_f32_dpp v146, v146, v146 quad_perm:[2,3,0,1] row_mask:0xf bank_mask:0xf bound_ctrl:1
	s_waitcnt lgkmcnt(12)
	v_pk_mul_f32 v[176:177], v[176:177], v[184:185] op_sel_hi:[1,0]
	v_add_f32_dpp v146, v146, v146 row_half_mirror row_mask:0xf bank_mask:0xf bound_ctrl:1
	v_pk_mul_f32 v[178:179], v[178:179], v[184:185] op_sel_hi:[1,0]
	s_nop 0
	v_add_f32_dpp v146, v146, v146 row_mirror row_mask:0xf bank_mask:0xf bound_ctrl:1
	v_pk_fma_f32 v[176:177], v[146:147], v[168:169], v[176:177] op_sel_hi:[0,1,1] neg_lo:[1,0,0] neg_hi:[1,0,0]
	v_pk_fma_f32 v[178:179], v[146:147], v[170:171], v[178:179] op_sel_hi:[0,1,1] neg_lo:[1,0,0] neg_hi:[1,0,0]
	v_pk_fma_f32 v[138:139], v[138:139], v[172:173], v[176:177]
	v_pk_fma_f32 v[140:141], v[140:141], v[174:175], v[178:179]
	v_pk_mul_f32 v[144:145], v[138:139], v[186:187]
	v_pk_fma_f32 v[144:145], v[140:141], v[188:189], v[144:145]
	v_add_f32 v146, v144, v145
	ds_read_b128 v[234:237], v10 offset:4864
	ds_read_b128 v[238:241], v10 offset:5120
	ds_read_b128 v[242:245], v10 offset:5376
	ds_read_b128 v[246:249], v10 offset:5632
	ds_read_b32 v250, v11 offset:4608
	ds_read_b128 v[164:167], v10 offset:6144
	v_add_f32_dpp v146, v146, v146 quad_perm:[1,0,3,2] row_mask:0xf bank_mask:0xf bound_ctrl:1
	v_pk_mul_f32 v[180:181], v[138:139], v[180:181]
	v_pk_fma_f32 v[180:181], v[140:141], v[182:183], v[180:181]
	v_add_f32_dpp v146, v146, v146 quad_perm:[2,3,0,1] row_mask:0xf bank_mask:0xf bound_ctrl:1
	s_waitcnt lgkmcnt(12)
	v_pk_mul_f32 v[198:199], v[198:199], v[206:207] op_sel_hi:[1,0]
	v_add_f32_dpp v146, v146, v146 row_half_mirror row_mask:0xf bank_mask:0xf bound_ctrl:1
	v_pk_mul_f32 v[200:201], v[200:201], v[206:207] op_sel_hi:[1,0]
	v_add_f32 v148, v180, v181
	v_add_f32_dpp v146, v146, v146 row_mirror row_mask:0xf bank_mask:0xf bound_ctrl:1
	v_pk_fma_f32 v[198:199], v[146:147], v[190:191], v[198:199] op_sel_hi:[0,1,1] neg_lo:[1,0,0] neg_hi:[1,0,0]
	v_pk_fma_f32 v[200:201], v[146:147], v[192:193], v[200:201] op_sel_hi:[0,1,1] neg_lo:[1,0,0] neg_hi:[1,0,0]
	v_pk_fma_f32 v[138:139], v[138:139], v[194:195], v[198:199]
	v_pk_fma_f32 v[140:141], v[140:141], v[196:197], v[200:201]
	v_pk_mul_f32 v[144:145], v[138:139], v[208:209]
	v_pk_fma_f32 v[144:145], v[140:141], v[210:211], v[144:145]
	v_add_f32 v146, v144, v145
	ds_read_b128 v[168:171], v10 offset:6400
	ds_read_b128 v[172:175], v10 offset:6656
	ds_read_b128 v[176:179], v10 offset:6912
	ds_read_b128 v[180:183], v10 offset:7168
	ds_read_b32 v184, v11 offset:6144
	ds_read_b128 v[186:189], v10 offset:7680
	v_add_f32_dpp v146, v146, v146 quad_perm:[1,0,3,2] row_mask:0xf bank_mask:0xf bound_ctrl:1
	v_pk_mul_f32 v[202:203], v[138:139], v[202:203]
	v_pk_fma_f32 v[202:203], v[140:141], v[204:205], v[202:203]
	v_add_f32_dpp v146, v146, v146 quad_perm:[2,3,0,1] row_mask:0xf bank_mask:0xf bound_ctrl:1
	s_waitcnt lgkmcnt(12)
	v_pk_mul_f32 v[220:221], v[220:221], v[228:229] op_sel_hi:[1,0]
	v_add_f32_dpp v146, v146, v146 row_half_mirror row_mask:0xf bank_mask:0xf bound_ctrl:1
	v_pk_mul_f32 v[222:223], v[222:223], v[228:229] op_sel_hi:[1,0]
	v_add_f32 v149, v202, v203
	v_add_f32_dpp v146, v146, v146 row_mirror row_mask:0xf bank_mask:0xf bound_ctrl:1
	v_pk_fma_f32 v[220:221], v[146:147], v[212:213], v[220:221] op_sel_hi:[0,1,1] neg_lo:[1,0,0] neg_hi:[1,0,0]
	v_pk_fma_f32 v[222:223], v[146:147], v[214:215], v[222:223] op_sel_hi:[0,1,1] neg_lo:[1,0,0] neg_hi:[1,0,0]
	v_pk_fma_f32 v[138:139], v[138:139], v[216:217], v[220:221]
	v_pk_fma_f32 v[140:141], v[140:141], v[218:219], v[222:223]
	v_pk_mul_f32 v[144:145], v[138:139], v[230:231]
	v_pk_fma_f32 v[144:145], v[140:141], v[232:233], v[144:145]
	v_add_f32 v146, v144, v145
	ds_read_b128 v[190:193], v10 offset:7936
	ds_read_b128 v[194:197], v10 offset:8192
	ds_read_b128 v[198:201], v10 offset:8448
	ds_read_b128 v[202:205], v10 offset:8704
	ds_read_b32 v206, v11 offset:7680
	ds_read_b128 v[208:211], v10 offset:9216
	v_add_f32_dpp v146, v146, v146 quad_perm:[1,0,3,2] row_mask:0xf bank_mask:0xf bound_ctrl:1
	v_pk_mul_f32 v[224:225], v[138:139], v[224:225]
	v_pk_fma_f32 v[224:225], v[140:141], v[226:227], v[224:225]
	v_add_f32_dpp v146, v146, v146 quad_perm:[2,3,0,1] row_mask:0xf bank_mask:0xf bound_ctrl:1
	s_waitcnt lgkmcnt(12)
	v_pk_mul_f32 v[242:243], v[242:243], v[250:251] op_sel_hi:[1,0]
	v_add_f32_dpp v146, v146, v146 row_half_mirror row_mask:0xf bank_mask:0xf bound_ctrl:1
	v_pk_mul_f32 v[244:245], v[244:245], v[250:251] op_sel_hi:[1,0]
	v_add_f32 v150, v224, v225
	v_add_f32_dpp v146, v146, v146 row_mirror row_mask:0xf bank_mask:0xf bound_ctrl:1
	v_pk_fma_f32 v[242:243], v[146:147], v[234:235], v[242:243] op_sel_hi:[0,1,1] neg_lo:[1,0,0] neg_hi:[1,0,0]
	v_pk_fma_f32 v[244:245], v[146:147], v[236:237], v[244:245] op_sel_hi:[0,1,1] neg_lo:[1,0,0] neg_hi:[1,0,0]
	v_pk_fma_f32 v[138:139], v[138:139], v[238:239], v[242:243]
	v_pk_fma_f32 v[140:141], v[140:141], v[240:241], v[244:245]
	v_pk_mul_f32 v[144:145], v[138:139], v[164:165]
	v_pk_fma_f32 v[144:145], v[140:141], v[166:167], v[144:145]
	v_add_f32 v146, v144, v145
	ds_read_b128 v[212:215], v10 offset:9472
	ds_read_b128 v[216:219], v10 offset:9728
	ds_read_b128 v[220:223], v10 offset:9984
	ds_read_b128 v[224:227], v10 offset:10240
	ds_read_b32 v228, v11 offset:9216
	ds_read_b128 v[230:233], v10 offset:10752
	v_add_f32_dpp v146, v146, v146 quad_perm:[1,0,3,2] row_mask:0xf bank_mask:0xf bound_ctrl:1
	v_pk_mul_f32 v[246:247], v[138:139], v[246:247]
	v_pk_fma_f32 v[246:247], v[140:141], v[248:249], v[246:247]
	v_add_f32_dpp v146, v146, v146 quad_perm:[2,3,0,1] row_mask:0xf bank_mask:0xf bound_ctrl:1
	s_waitcnt lgkmcnt(12)
	v_pk_mul_f32 v[176:177], v[176:177], v[184:185] op_sel_hi:[1,0]
	v_add_f32_dpp v146, v146, v146 row_half_mirror row_mask:0xf bank_mask:0xf bound_ctrl:1
	v_pk_mul_f32 v[178:179], v[178:179], v[184:185] op_sel_hi:[1,0]
	v_add_f32 v151, v246, v247
	v_add_f32_dpp v146, v146, v146 row_mirror row_mask:0xf bank_mask:0xf bound_ctrl:1
	v_pk_fma_f32 v[176:177], v[146:147], v[168:169], v[176:177] op_sel_hi:[0,1,1] neg_lo:[1,0,0] neg_hi:[1,0,0]
	v_pk_fma_f32 v[178:179], v[146:147], v[170:171], v[178:179] op_sel_hi:[0,1,1] neg_lo:[1,0,0] neg_hi:[1,0,0]
	v_pk_fma_f32 v[138:139], v[138:139], v[172:173], v[176:177]
	v_pk_fma_f32 v[140:141], v[140:141], v[174:175], v[178:179]
	v_pk_mul_f32 v[144:145], v[138:139], v[186:187]
	v_pk_fma_f32 v[144:145], v[140:141], v[188:189], v[144:145]
	v_add_f32 v146, v144, v145
	ds_read_b128 v[234:237], v10 offset:11008
	ds_read_b128 v[238:241], v10 offset:11264
	ds_read_b128 v[242:245], v10 offset:11520
	ds_read_b128 v[246:249], v10 offset:11776
	ds_read_b32 v250, v11 offset:10752
	ds_read_b128 v[164:167], v10 offset:12288
	v_add_f32_dpp v146, v146, v146 quad_perm:[1,0,3,2] row_mask:0xf bank_mask:0xf bound_ctrl:1
	v_pk_mul_f32 v[180:181], v[138:139], v[180:181]
	v_pk_fma_f32 v[180:181], v[140:141], v[182:183], v[180:181]
	v_add_f32_dpp v146, v146, v146 quad_perm:[2,3,0,1] row_mask:0xf bank_mask:0xf bound_ctrl:1
	s_waitcnt lgkmcnt(12)
	v_pk_mul_f32 v[198:199], v[198:199], v[206:207] op_sel_hi:[1,0]
	v_add_f32_dpp v146, v146, v146 row_half_mirror row_mask:0xf bank_mask:0xf bound_ctrl:1
	v_pk_mul_f32 v[200:201], v[200:201], v[206:207] op_sel_hi:[1,0]
	v_add_f32 v152, v180, v181
	v_add_f32_dpp v146, v146, v146 row_mirror row_mask:0xf bank_mask:0xf bound_ctrl:1
	v_pk_fma_f32 v[198:199], v[146:147], v[190:191], v[198:199] op_sel_hi:[0,1,1] neg_lo:[1,0,0] neg_hi:[1,0,0]
	v_pk_fma_f32 v[200:201], v[146:147], v[192:193], v[200:201] op_sel_hi:[0,1,1] neg_lo:[1,0,0] neg_hi:[1,0,0]
	v_pk_fma_f32 v[138:139], v[138:139], v[194:195], v[198:199]
	v_pk_fma_f32 v[140:141], v[140:141], v[196:197], v[200:201]
	v_pk_mul_f32 v[144:145], v[138:139], v[208:209]
	v_pk_fma_f32 v[144:145], v[140:141], v[210:211], v[144:145]
	v_add_f32 v146, v144, v145
	ds_read_b128 v[168:171], v10 offset:12544
	ds_read_b128 v[172:175], v10 offset:12800
	ds_read_b128 v[176:179], v10 offset:13056
	ds_read_b128 v[180:183], v10 offset:13312
	ds_read_b32 v184, v11 offset:12288
	ds_read_b128 v[186:189], v10 offset:13824
	v_add_f32_dpp v146, v146, v146 quad_perm:[1,0,3,2] row_mask:0xf bank_mask:0xf bound_ctrl:1
	v_pk_mul_f32 v[202:203], v[138:139], v[202:203]
	v_pk_fma_f32 v[202:203], v[140:141], v[204:205], v[202:203]
	v_add_f32_dpp v146, v146, v146 quad_perm:[2,3,0,1] row_mask:0xf bank_mask:0xf bound_ctrl:1
	s_waitcnt lgkmcnt(12)
	v_pk_mul_f32 v[220:221], v[220:221], v[228:229] op_sel_hi:[1,0]
	v_add_f32_dpp v146, v146, v146 row_half_mirror row_mask:0xf bank_mask:0xf bound_ctrl:1
	v_pk_mul_f32 v[222:223], v[222:223], v[228:229] op_sel_hi:[1,0]
	v_add_f32 v153, v202, v203
	v_add_f32_dpp v146, v146, v146 row_mirror row_mask:0xf bank_mask:0xf bound_ctrl:1
	v_pk_fma_f32 v[220:221], v[146:147], v[212:213], v[220:221] op_sel_hi:[0,1,1] neg_lo:[1,0,0] neg_hi:[1,0,0]
	v_pk_fma_f32 v[222:223], v[146:147], v[214:215], v[222:223] op_sel_hi:[0,1,1] neg_lo:[1,0,0] neg_hi:[1,0,0]
	v_pk_fma_f32 v[138:139], v[138:139], v[216:217], v[220:221]
	v_pk_fma_f32 v[140:141], v[140:141], v[218:219], v[222:223]
	v_pk_mul_f32 v[144:145], v[138:139], v[230:231]
	v_pk_fma_f32 v[144:145], v[140:141], v[232:233], v[144:145]
	v_add_f32 v146, v144, v145
	ds_read_b128 v[190:193], v10 offset:14080
	ds_read_b128 v[194:197], v10 offset:14336
	ds_read_b128 v[198:201], v10 offset:14592
	ds_read_b128 v[202:205], v10 offset:14848
	ds_read_b32 v206, v11 offset:13824
	ds_read_b128 v[208:211], v10 offset:15360
	v_add_f32_dpp v146, v146, v146 quad_perm:[1,0,3,2] row_mask:0xf bank_mask:0xf bound_ctrl:1
	v_pk_mul_f32 v[224:225], v[138:139], v[224:225]
	v_pk_fma_f32 v[224:225], v[140:141], v[226:227], v[224:225]
	v_add_f32_dpp v146, v146, v146 quad_perm:[2,3,0,1] row_mask:0xf bank_mask:0xf bound_ctrl:1
	s_waitcnt lgkmcnt(12)
	v_pk_mul_f32 v[242:243], v[242:243], v[250:251] op_sel_hi:[1,0]
	v_add_f32_dpp v146, v146, v146 row_half_mirror row_mask:0xf bank_mask:0xf bound_ctrl:1
	v_pk_mul_f32 v[244:245], v[244:245], v[250:251] op_sel_hi:[1,0]
	v_add_f32 v154, v224, v225
	v_add_f32_dpp v146, v146, v146 row_mirror row_mask:0xf bank_mask:0xf bound_ctrl:1
	v_pk_fma_f32 v[242:243], v[146:147], v[234:235], v[242:243] op_sel_hi:[0,1,1] neg_lo:[1,0,0] neg_hi:[1,0,0]
	v_pk_fma_f32 v[244:245], v[146:147], v[236:237], v[244:245] op_sel_hi:[0,1,1] neg_lo:[1,0,0] neg_hi:[1,0,0]
	v_pk_fma_f32 v[138:139], v[138:139], v[238:239], v[242:243]
	v_pk_fma_f32 v[140:141], v[140:141], v[240:241], v[244:245]
	v_pk_mul_f32 v[144:145], v[138:139], v[164:165]
	v_pk_fma_f32 v[144:145], v[140:141], v[166:167], v[144:145]
	v_add_f32 v146, v144, v145
	ds_read_b128 v[212:215], v10 offset:15616
	ds_read_b128 v[216:219], v10 offset:15872
	ds_read_b128 v[220:223], v10 offset:16128
	ds_read_b128 v[224:227], v10 offset:16384
	ds_read_b32 v228, v11 offset:15360
	ds_read_b128 v[230:233], v10 offset:16896
	v_add_f32_dpp v146, v146, v146 quad_perm:[1,0,3,2] row_mask:0xf bank_mask:0xf bound_ctrl:1
	v_pk_mul_f32 v[246:247], v[138:139], v[246:247]
	v_pk_fma_f32 v[246:247], v[140:141], v[248:249], v[246:247]
	v_add_f32_dpp v146, v146, v146 quad_perm:[2,3,0,1] row_mask:0xf bank_mask:0xf bound_ctrl:1
	s_waitcnt lgkmcnt(12)
	v_pk_mul_f32 v[176:177], v[176:177], v[184:185] op_sel_hi:[1,0]
	v_add_f32_dpp v146, v146, v146 row_half_mirror row_mask:0xf bank_mask:0xf bound_ctrl:1
	v_pk_mul_f32 v[178:179], v[178:179], v[184:185] op_sel_hi:[1,0]
	v_add_f32 v155, v246, v247
	v_add_f32_dpp v146, v146, v146 row_mirror row_mask:0xf bank_mask:0xf bound_ctrl:1
	v_pk_fma_f32 v[176:177], v[146:147], v[168:169], v[176:177] op_sel_hi:[0,1,1] neg_lo:[1,0,0] neg_hi:[1,0,0]
	v_pk_fma_f32 v[178:179], v[146:147], v[170:171], v[178:179] op_sel_hi:[0,1,1] neg_lo:[1,0,0] neg_hi:[1,0,0]
	v_pk_fma_f32 v[138:139], v[138:139], v[172:173], v[176:177]
	v_pk_fma_f32 v[140:141], v[140:141], v[174:175], v[178:179]
	v_pk_mul_f32 v[144:145], v[138:139], v[186:187]
	v_pk_fma_f32 v[144:145], v[140:141], v[188:189], v[144:145]
	v_add_f32 v146, v144, v145
	ds_read_b128 v[234:237], v10 offset:17152
	ds_read_b128 v[238:241], v10 offset:17408
	ds_read_b128 v[242:245], v10 offset:17664
	ds_read_b128 v[246:249], v10 offset:17920
	ds_read_b32 v250, v11 offset:16896
	ds_read_b128 v[164:167], v10 offset:18432
	v_add_f32_dpp v146, v146, v146 quad_perm:[1,0,3,2] row_mask:0xf bank_mask:0xf bound_ctrl:1
	v_pk_mul_f32 v[180:181], v[138:139], v[180:181]
	v_pk_fma_f32 v[180:181], v[140:141], v[182:183], v[180:181]
	v_add_f32_dpp v146, v146, v146 quad_perm:[2,3,0,1] row_mask:0xf bank_mask:0xf bound_ctrl:1
	s_waitcnt lgkmcnt(12)
	v_pk_mul_f32 v[198:199], v[198:199], v[206:207] op_sel_hi:[1,0]
	v_add_f32_dpp v146, v146, v146 row_half_mirror row_mask:0xf bank_mask:0xf bound_ctrl:1
	v_pk_mul_f32 v[200:201], v[200:201], v[206:207] op_sel_hi:[1,0]
	v_add_f32 v156, v180, v181
	v_add_f32_dpp v146, v146, v146 row_mirror row_mask:0xf bank_mask:0xf bound_ctrl:1
	v_pk_fma_f32 v[198:199], v[146:147], v[190:191], v[198:199] op_sel_hi:[0,1,1] neg_lo:[1,0,0] neg_hi:[1,0,0]
	v_pk_fma_f32 v[200:201], v[146:147], v[192:193], v[200:201] op_sel_hi:[0,1,1] neg_lo:[1,0,0] neg_hi:[1,0,0]
	v_pk_fma_f32 v[138:139], v[138:139], v[194:195], v[198:199]
	v_pk_fma_f32 v[140:141], v[140:141], v[196:197], v[200:201]
	v_pk_mul_f32 v[144:145], v[138:139], v[208:209]
	v_pk_fma_f32 v[144:145], v[140:141], v[210:211], v[144:145]
	v_add_f32 v146, v144, v145
	ds_read_b128 v[168:171], v10 offset:18688
	ds_read_b128 v[172:175], v10 offset:18944
	ds_read_b128 v[176:179], v10 offset:19200
	ds_read_b128 v[180:183], v10 offset:19456
	ds_read_b32 v184, v11 offset:18432
	ds_read_b128 v[186:189], v10 offset:19968
	v_add_f32_dpp v146, v146, v146 quad_perm:[1,0,3,2] row_mask:0xf bank_mask:0xf bound_ctrl:1
	v_pk_mul_f32 v[202:203], v[138:139], v[202:203]
	v_pk_fma_f32 v[202:203], v[140:141], v[204:205], v[202:203]
	v_add_f32_dpp v146, v146, v146 quad_perm:[2,3,0,1] row_mask:0xf bank_mask:0xf bound_ctrl:1
	s_waitcnt lgkmcnt(12)
	v_pk_mul_f32 v[220:221], v[220:221], v[228:229] op_sel_hi:[1,0]
	v_add_f32_dpp v146, v146, v146 row_half_mirror row_mask:0xf bank_mask:0xf bound_ctrl:1
	v_pk_mul_f32 v[222:223], v[222:223], v[228:229] op_sel_hi:[1,0]
	v_add_f32 v157, v202, v203
	v_add_f32_dpp v146, v146, v146 row_mirror row_mask:0xf bank_mask:0xf bound_ctrl:1
	v_pk_fma_f32 v[220:221], v[146:147], v[212:213], v[220:221] op_sel_hi:[0,1,1] neg_lo:[1,0,0] neg_hi:[1,0,0]
	v_pk_fma_f32 v[222:223], v[146:147], v[214:215], v[222:223] op_sel_hi:[0,1,1] neg_lo:[1,0,0] neg_hi:[1,0,0]
	v_pk_fma_f32 v[138:139], v[138:139], v[216:217], v[220:221]
	v_pk_fma_f32 v[140:141], v[140:141], v[218:219], v[222:223]
	v_pk_mul_f32 v[144:145], v[138:139], v[230:231]
	v_pk_fma_f32 v[144:145], v[140:141], v[232:233], v[144:145]
	v_add_f32 v146, v144, v145
	ds_read_b128 v[190:193], v10 offset:20224
	ds_read_b128 v[194:197], v10 offset:20480
	ds_read_b128 v[198:201], v10 offset:20736
	ds_read_b128 v[202:205], v10 offset:20992
	ds_read_b32 v206, v11 offset:19968
	ds_read_b128 v[208:211], v10 offset:21504
	v_add_f32_dpp v146, v146, v146 quad_perm:[1,0,3,2] row_mask:0xf bank_mask:0xf bound_ctrl:1
	v_pk_mul_f32 v[224:225], v[138:139], v[224:225]
	v_pk_fma_f32 v[224:225], v[140:141], v[226:227], v[224:225]
	v_add_f32_dpp v146, v146, v146 quad_perm:[2,3,0,1] row_mask:0xf bank_mask:0xf bound_ctrl:1
	s_waitcnt lgkmcnt(12)
	v_pk_mul_f32 v[242:243], v[242:243], v[250:251] op_sel_hi:[1,0]
	v_add_f32_dpp v146, v146, v146 row_half_mirror row_mask:0xf bank_mask:0xf bound_ctrl:1
	v_pk_mul_f32 v[244:245], v[244:245], v[250:251] op_sel_hi:[1,0]
	v_add_f32 v158, v224, v225
	v_add_f32_dpp v146, v146, v146 row_mirror row_mask:0xf bank_mask:0xf bound_ctrl:1
	v_pk_fma_f32 v[242:243], v[146:147], v[234:235], v[242:243] op_sel_hi:[0,1,1] neg_lo:[1,0,0] neg_hi:[1,0,0]
	v_pk_fma_f32 v[244:245], v[146:147], v[236:237], v[244:245] op_sel_hi:[0,1,1] neg_lo:[1,0,0] neg_hi:[1,0,0]
	v_pk_fma_f32 v[138:139], v[138:139], v[238:239], v[242:243]
	v_pk_fma_f32 v[140:141], v[140:141], v[240:241], v[244:245]
	v_pk_mul_f32 v[144:145], v[138:139], v[164:165]
	v_pk_fma_f32 v[144:145], v[140:141], v[166:167], v[144:145]
	v_add_f32 v146, v144, v145
	ds_read_b128 v[212:215], v10 offset:21760
	ds_read_b128 v[216:219], v10 offset:22016
	ds_read_b128 v[220:223], v10 offset:22272
	ds_read_b128 v[224:227], v10 offset:22528
	ds_read_b32 v228, v11 offset:21504
	ds_read_b128 v[230:233], v10 offset:23040
	v_add_f32_dpp v146, v146, v146 quad_perm:[1,0,3,2] row_mask:0xf bank_mask:0xf bound_ctrl:1
	v_pk_mul_f32 v[246:247], v[138:139], v[246:247]
	v_pk_fma_f32 v[246:247], v[140:141], v[248:249], v[246:247]
	v_add_f32_dpp v146, v146, v146 quad_perm:[2,3,0,1] row_mask:0xf bank_mask:0xf bound_ctrl:1
	s_waitcnt lgkmcnt(12)
	v_pk_mul_f32 v[176:177], v[176:177], v[184:185] op_sel_hi:[1,0]
	v_add_f32_dpp v146, v146, v146 row_half_mirror row_mask:0xf bank_mask:0xf bound_ctrl:1
	v_pk_mul_f32 v[178:179], v[178:179], v[184:185] op_sel_hi:[1,0]
	v_add_f32 v159, v246, v247
	v_add_f32_dpp v146, v146, v146 row_mirror row_mask:0xf bank_mask:0xf bound_ctrl:1
	v_pk_fma_f32 v[176:177], v[146:147], v[168:169], v[176:177] op_sel_hi:[0,1,1] neg_lo:[1,0,0] neg_hi:[1,0,0]
	v_pk_fma_f32 v[178:179], v[146:147], v[170:171], v[178:179] op_sel_hi:[0,1,1] neg_lo:[1,0,0] neg_hi:[1,0,0]
	v_pk_fma_f32 v[138:139], v[138:139], v[172:173], v[176:177]
	v_pk_fma_f32 v[140:141], v[140:141], v[174:175], v[178:179]
	v_pk_mul_f32 v[144:145], v[138:139], v[186:187]
	v_pk_fma_f32 v[144:145], v[140:141], v[188:189], v[144:145]
	v_add_f32 v146, v144, v145
	ds_read_b128 v[234:237], v10 offset:23296
	ds_read_b128 v[238:241], v10 offset:23552
	ds_read_b128 v[242:245], v10 offset:23808
	ds_read_b128 v[246:249], v10 offset:24064
	ds_read_b32 v250, v11 offset:23040
	ds_read_b128 v[164:167], v10 offset:24576
	v_add_f32_dpp v146, v146, v146 quad_perm:[1,0,3,2] row_mask:0xf bank_mask:0xf bound_ctrl:1
	v_pk_mul_f32 v[180:181], v[138:139], v[180:181]
	v_pk_fma_f32 v[180:181], v[140:141], v[182:183], v[180:181]
	v_add_f32_dpp v146, v146, v146 quad_perm:[2,3,0,1] row_mask:0xf bank_mask:0xf bound_ctrl:1
	s_waitcnt lgkmcnt(12)
	v_pk_mul_f32 v[198:199], v[198:199], v[206:207] op_sel_hi:[1,0]
	v_add_f32_dpp v146, v146, v146 row_half_mirror row_mask:0xf bank_mask:0xf bound_ctrl:1
	v_pk_mul_f32 v[200:201], v[200:201], v[206:207] op_sel_hi:[1,0]
	v_add_f32 v160, v180, v181
	v_add_f32_dpp v146, v146, v146 row_mirror row_mask:0xf bank_mask:0xf bound_ctrl:1
	v_pk_fma_f32 v[198:199], v[146:147], v[190:191], v[198:199] op_sel_hi:[0,1,1] neg_lo:[1,0,0] neg_hi:[1,0,0]
	v_pk_fma_f32 v[200:201], v[146:147], v[192:193], v[200:201] op_sel_hi:[0,1,1] neg_lo:[1,0,0] neg_hi:[1,0,0]
	v_pk_fma_f32 v[138:139], v[138:139], v[194:195], v[198:199]
	v_pk_fma_f32 v[140:141], v[140:141], v[196:197], v[200:201]
	v_pk_mul_f32 v[144:145], v[138:139], v[208:209]
	v_pk_fma_f32 v[144:145], v[140:141], v[210:211], v[144:145]
	v_add_f32 v146, v144, v145
	ds_read_b128 v[168:171], v10 offset:24832
	ds_read_b128 v[172:175], v10 offset:25088
	ds_read_b128 v[176:179], v10 offset:25344
	ds_read_b128 v[180:183], v10 offset:25600
	ds_read_b32 v184, v11 offset:24576
	ds_read_b128 v[186:189], v10 offset:26112
	v_add_f32_dpp v146, v146, v146 quad_perm:[1,0,3,2] row_mask:0xf bank_mask:0xf bound_ctrl:1
	v_pk_mul_f32 v[202:203], v[138:139], v[202:203]
	v_pk_fma_f32 v[202:203], v[140:141], v[204:205], v[202:203]
	v_add_f32_dpp v146, v146, v146 quad_perm:[2,3,0,1] row_mask:0xf bank_mask:0xf bound_ctrl:1
	s_waitcnt lgkmcnt(12)
	v_pk_mul_f32 v[220:221], v[220:221], v[228:229] op_sel_hi:[1,0]
	v_add_f32_dpp v146, v146, v146 row_half_mirror row_mask:0xf bank_mask:0xf bound_ctrl:1
	v_pk_mul_f32 v[222:223], v[222:223], v[228:229] op_sel_hi:[1,0]
	v_add_f32 v161, v202, v203
	v_add_f32_dpp v146, v146, v146 row_mirror row_mask:0xf bank_mask:0xf bound_ctrl:1
	v_pk_fma_f32 v[220:221], v[146:147], v[212:213], v[220:221] op_sel_hi:[0,1,1] neg_lo:[1,0,0] neg_hi:[1,0,0]
	v_pk_fma_f32 v[222:223], v[146:147], v[214:215], v[222:223] op_sel_hi:[0,1,1] neg_lo:[1,0,0] neg_hi:[1,0,0]
	v_pk_fma_f32 v[138:139], v[138:139], v[216:217], v[220:221]
	v_pk_fma_f32 v[140:141], v[140:141], v[218:219], v[222:223]
	v_pk_mul_f32 v[144:145], v[138:139], v[230:231]
	v_pk_fma_f32 v[144:145], v[140:141], v[232:233], v[144:145]
	v_add_f32 v146, v144, v145
	ds_read_b128 v[190:193], v10 offset:26368
	ds_read_b128 v[194:197], v10 offset:26624
	ds_read_b128 v[198:201], v10 offset:26880
	ds_read_b128 v[202:205], v10 offset:27136
	ds_read_b32 v206, v11 offset:26112
	ds_read_b128 v[208:211], v10 offset:27648
	v_add_f32_dpp v146, v146, v146 quad_perm:[1,0,3,2] row_mask:0xf bank_mask:0xf bound_ctrl:1
	v_pk_mul_f32 v[224:225], v[138:139], v[224:225]
	v_pk_fma_f32 v[224:225], v[140:141], v[226:227], v[224:225]
	v_add_f32_dpp v146, v146, v146 quad_perm:[2,3,0,1] row_mask:0xf bank_mask:0xf bound_ctrl:1
	s_waitcnt lgkmcnt(12)
	v_pk_mul_f32 v[242:243], v[242:243], v[250:251] op_sel_hi:[1,0]
	v_add_f32_dpp v146, v146, v146 row_half_mirror row_mask:0xf bank_mask:0xf bound_ctrl:1
	v_pk_mul_f32 v[244:245], v[244:245], v[250:251] op_sel_hi:[1,0]
	v_add_f32 v162, v224, v225
	v_add_f32_dpp v146, v146, v146 row_mirror row_mask:0xf bank_mask:0xf bound_ctrl:1
	v_pk_fma_f32 v[242:243], v[146:147], v[234:235], v[242:243] op_sel_hi:[0,1,1] neg_lo:[1,0,0] neg_hi:[1,0,0]
	v_pk_fma_f32 v[244:245], v[146:147], v[236:237], v[244:245] op_sel_hi:[0,1,1] neg_lo:[1,0,0] neg_hi:[1,0,0]
	v_pk_fma_f32 v[138:139], v[138:139], v[238:239], v[242:243]
	v_pk_fma_f32 v[140:141], v[140:141], v[240:241], v[244:245]
	v_pk_mul_f32 v[144:145], v[138:139], v[164:165]
	v_pk_fma_f32 v[144:145], v[140:141], v[166:167], v[144:145]
	v_add_f32 v146, v144, v145
	ds_read_b128 v[212:215], v10 offset:27904
	ds_read_b128 v[216:219], v10 offset:28160
	ds_read_b128 v[220:223], v10 offset:28416
	ds_read_b128 v[224:227], v10 offset:28672
	ds_read_b32 v228, v11 offset:27648
	ds_read_b128 v[230:233], v10 offset:29184
	v_add_f32_dpp v146, v146, v146 quad_perm:[1,0,3,2] row_mask:0xf bank_mask:0xf bound_ctrl:1
	v_pk_mul_f32 v[246:247], v[138:139], v[246:247]
	v_pk_fma_f32 v[246:247], v[140:141], v[248:249], v[246:247]
	v_add_f32_dpp v146, v146, v146 quad_perm:[2,3,0,1] row_mask:0xf bank_mask:0xf bound_ctrl:1
	s_waitcnt lgkmcnt(12)
	v_pk_mul_f32 v[176:177], v[176:177], v[184:185] op_sel_hi:[1,0]
	v_add_f32_dpp v146, v146, v146 row_half_mirror row_mask:0xf bank_mask:0xf bound_ctrl:1
	v_pk_mul_f32 v[178:179], v[178:179], v[184:185] op_sel_hi:[1,0]
	v_add_f32 v163, v246, v247
	v_add_f32_dpp v146, v146, v146 row_mirror row_mask:0xf bank_mask:0xf bound_ctrl:1
	v_pk_fma_f32 v[176:177], v[146:147], v[168:169], v[176:177] op_sel_hi:[0,1,1] neg_lo:[1,0,0] neg_hi:[1,0,0]
	v_pk_fma_f32 v[178:179], v[146:147], v[170:171], v[178:179] op_sel_hi:[0,1,1] neg_lo:[1,0,0] neg_hi:[1,0,0]
	v_pk_fma_f32 v[138:139], v[138:139], v[172:173], v[176:177]
	v_pk_fma_f32 v[140:141], v[140:141], v[174:175], v[178:179]
	v_pk_mul_f32 v[144:145], v[138:139], v[186:187]
	v_pk_fma_f32 v[144:145], v[140:141], v[188:189], v[144:145]
	v_add_f32 v146, v144, v145
	v_add_f32_dpp v102, v148, v148 row_mirror row_mask:0xf bank_mask:0x3 bound_ctrl:1
	v_add_f32_dpp v102, v156, v156 row_mirror row_mask:0xf bank_mask:0xc bound_ctrl:1
	v_add_f32_dpp v103, v149, v149 row_mirror row_mask:0xf bank_mask:0x3 bound_ctrl:1
	v_add_f32_dpp v103, v157, v157 row_mirror row_mask:0xf bank_mask:0xc bound_ctrl:1
	v_add_f32_dpp v104, v150, v150 row_mirror row_mask:0xf bank_mask:0x3 bound_ctrl:1
	v_add_f32_dpp v104, v158, v158 row_mirror row_mask:0xf bank_mask:0xc bound_ctrl:1
	v_add_f32_dpp v105, v151, v151 row_mirror row_mask:0xf bank_mask:0x3 bound_ctrl:1
	v_add_f32_dpp v105, v159, v159 row_mirror row_mask:0xf bank_mask:0xc bound_ctrl:1
	v_add_f32_dpp v106, v152, v152 row_mirror row_mask:0xf bank_mask:0x3 bound_ctrl:1
	v_add_f32_dpp v106, v160, v160 row_mirror row_mask:0xf bank_mask:0xc bound_ctrl:1
	v_add_f32_dpp v107, v153, v153 row_mirror row_mask:0xf bank_mask:0x3 bound_ctrl:1
	v_add_f32_dpp v107, v161, v161 row_mirror row_mask:0xf bank_mask:0xc bound_ctrl:1
	v_add_f32_dpp v108, v154, v154 row_mirror row_mask:0xf bank_mask:0x3 bound_ctrl:1
	v_add_f32_dpp v108, v162, v162 row_mirror row_mask:0xf bank_mask:0xc bound_ctrl:1
	v_add_f32_dpp v109, v155, v155 row_mirror row_mask:0xf bank_mask:0x3 bound_ctrl:1
	v_add_f32_dpp v109, v163, v163 row_mirror row_mask:0xf bank_mask:0xc bound_ctrl:1
	v_add_f32_dpp v110, v102, v102 row_half_mirror row_mask:0xf bank_mask:0x5 bound_ctrl:1
	v_add_f32_dpp v110, v106, v106 row_half_mirror row_mask:0xf bank_mask:0xa bound_ctrl:1
	v_add_f32_dpp v111, v103, v103 row_half_mirror row_mask:0xf bank_mask:0x5 bound_ctrl:1
	v_add_f32_dpp v111, v107, v107 row_half_mirror row_mask:0xf bank_mask:0xa bound_ctrl:1
	v_add_f32_dpp v112, v104, v104 row_half_mirror row_mask:0xf bank_mask:0x5 bound_ctrl:1
	v_add_f32_dpp v112, v108, v108 row_half_mirror row_mask:0xf bank_mask:0xa bound_ctrl:1
	v_add_f32_dpp v113, v105, v105 row_half_mirror row_mask:0xf bank_mask:0x5 bound_ctrl:1
	v_add_f32_dpp v113, v109, v109 row_half_mirror row_mask:0xf bank_mask:0xa bound_ctrl:1
	s_mov_b32 vcc_lo, 0xcccccccc
	s_mov_b32 vcc_hi, 0xcccccccc
	v_cndmask_b32 v116, v112, v110, vcc
	v_cndmask_b32 v117, v113, v111, vcc
	v_cndmask_b32 v114, v110, v112, vcc
	v_cndmask_b32 v115, v111, v113, vcc
	v_add_f32_dpp v114, v116, v114 quad_perm:[2,3,0,1] row_mask:0xf bank_mask:0xf bound_ctrl:1
	v_add_f32_dpp v115, v117, v115 quad_perm:[2,3,0,1] row_mask:0xf bank_mask:0xf bound_ctrl:1
	s_mov_b32 vcc_lo, 0xaaaaaaaa
	s_mov_b32 vcc_hi, 0xaaaaaaaa
	v_cndmask_b32 v116, v115, v114, vcc
	v_cndmask_b32 v117, v114, v115, vcc
	s_nop 0
	v_add_f32_dpp v18, v116, v117 quad_perm:[1,0,3,2] row_mask:0xf bank_mask:0xf bound_ctrl:1
	ds_read_b128 v[234:237], v10 offset:29440
	ds_read_b128 v[238:241], v10 offset:29696
	ds_read_b128 v[242:245], v10 offset:29952
	ds_read_b128 v[246:249], v10 offset:30208
	ds_read_b32 v250, v11 offset:29184
	ds_read_b128 v[164:167], v10 offset:30720
	v_add_f32_dpp v146, v146, v146 quad_perm:[1,0,3,2] row_mask:0xf bank_mask:0xf bound_ctrl:1
	v_pk_mul_f32 v[180:181], v[138:139], v[180:181]
	v_pk_fma_f32 v[180:181], v[140:141], v[182:183], v[180:181]
	v_add_f32_dpp v146, v146, v146 quad_perm:[2,3,0,1] row_mask:0xf bank_mask:0xf bound_ctrl:1
	s_waitcnt lgkmcnt(12)
	v_pk_mul_f32 v[198:199], v[198:199], v[206:207] op_sel_hi:[1,0]
	v_add_f32_dpp v146, v146, v146 row_half_mirror row_mask:0xf bank_mask:0xf bound_ctrl:1
	v_pk_mul_f32 v[200:201], v[200:201], v[206:207] op_sel_hi:[1,0]
	v_add_f32 v148, v180, v181
	v_add_f32_dpp v146, v146, v146 row_mirror row_mask:0xf bank_mask:0xf bound_ctrl:1
	v_pk_fma_f32 v[198:199], v[146:147], v[190:191], v[198:199] op_sel_hi:[0,1,1] neg_lo:[1,0,0] neg_hi:[1,0,0]
	v_pk_fma_f32 v[200:201], v[146:147], v[192:193], v[200:201] op_sel_hi:[0,1,1] neg_lo:[1,0,0] neg_hi:[1,0,0]
	v_pk_fma_f32 v[138:139], v[138:139], v[194:195], v[198:199]
	v_pk_fma_f32 v[140:141], v[140:141], v[196:197], v[200:201]
	v_pk_mul_f32 v[144:145], v[138:139], v[208:209]
	v_pk_fma_f32 v[144:145], v[140:141], v[210:211], v[144:145]
	v_add_f32 v146, v144, v145
	ds_read_b128 v[168:171], v10 offset:30976
	ds_read_b128 v[172:175], v10 offset:31232
	ds_read_b128 v[176:179], v10 offset:31488
	ds_read_b128 v[180:183], v10 offset:31744
	ds_read_b32 v184, v11 offset:30720
	ds_read_b128 v[186:189], v10 offset:32256
	v_add_f32_dpp v146, v146, v146 quad_perm:[1,0,3,2] row_mask:0xf bank_mask:0xf bound_ctrl:1
	v_pk_mul_f32 v[202:203], v[138:139], v[202:203]
	v_pk_fma_f32 v[202:203], v[140:141], v[204:205], v[202:203]
	v_add_f32_dpp v146, v146, v146 quad_perm:[2,3,0,1] row_mask:0xf bank_mask:0xf bound_ctrl:1
	s_waitcnt lgkmcnt(12)
	v_pk_mul_f32 v[220:221], v[220:221], v[228:229] op_sel_hi:[1,0]
	v_add_f32_dpp v146, v146, v146 row_half_mirror row_mask:0xf bank_mask:0xf bound_ctrl:1
	v_pk_mul_f32 v[222:223], v[222:223], v[228:229] op_sel_hi:[1,0]
	v_add_f32 v149, v202, v203
	v_add_f32_dpp v146, v146, v146 row_mirror row_mask:0xf bank_mask:0xf bound_ctrl:1
	v_pk_fma_f32 v[220:221], v[146:147], v[212:213], v[220:221] op_sel_hi:[0,1,1] neg_lo:[1,0,0] neg_hi:[1,0,0]
	v_pk_fma_f32 v[222:223], v[146:147], v[214:215], v[222:223] op_sel_hi:[0,1,1] neg_lo:[1,0,0] neg_hi:[1,0,0]
	v_pk_fma_f32 v[138:139], v[138:139], v[216:217], v[220:221]
	v_pk_fma_f32 v[140:141], v[140:141], v[218:219], v[222:223]
	v_pk_mul_f32 v[144:145], v[138:139], v[230:231]
	v_pk_fma_f32 v[144:145], v[140:141], v[232:233], v[144:145]
	v_add_f32 v146, v144, v145
	ds_read_b128 v[190:193], v10 offset:32512
	ds_read_b128 v[194:197], v10 offset:32768
	ds_read_b128 v[198:201], v10 offset:33024
	ds_read_b128 v[202:205], v10 offset:33280
	ds_read_b32 v206, v11 offset:32256
	ds_read_b128 v[208:211], v10 offset:33792
	v_add_f32_dpp v146, v146, v146 quad_perm:[1,0,3,2] row_mask:0xf bank_mask:0xf bound_ctrl:1
	v_pk_mul_f32 v[224:225], v[138:139], v[224:225]
	v_pk_fma_f32 v[224:225], v[140:141], v[226:227], v[224:225]
	v_add_f32_dpp v146, v146, v146 quad_perm:[2,3,0,1] row_mask:0xf bank_mask:0xf bound_ctrl:1
	s_waitcnt lgkmcnt(12)
	v_pk_mul_f32 v[242:243], v[242:243], v[250:251] op_sel_hi:[1,0]
	v_add_f32_dpp v146, v146, v146 row_half_mirror row_mask:0xf bank_mask:0xf bound_ctrl:1
	v_pk_mul_f32 v[244:245], v[244:245], v[250:251] op_sel_hi:[1,0]
	v_add_f32 v150, v224, v225
	v_add_f32_dpp v146, v146, v146 row_mirror row_mask:0xf bank_mask:0xf bound_ctrl:1
	v_pk_fma_f32 v[242:243], v[146:147], v[234:235], v[242:243] op_sel_hi:[0,1,1] neg_lo:[1,0,0] neg_hi:[1,0,0]
	v_pk_fma_f32 v[244:245], v[146:147], v[236:237], v[244:245] op_sel_hi:[0,1,1] neg_lo:[1,0,0] neg_hi:[1,0,0]
	v_pk_fma_f32 v[138:139], v[138:139], v[238:239], v[242:243]
	v_pk_fma_f32 v[140:141], v[140:141], v[240:241], v[244:245]
	v_pk_mul_f32 v[144:145], v[138:139], v[164:165]
	v_pk_fma_f32 v[144:145], v[140:141], v[166:167], v[144:145]
	v_add_f32 v146, v144, v145
	ds_read_b128 v[212:215], v10 offset:34048
	ds_read_b128 v[216:219], v10 offset:34304
	ds_read_b128 v[220:223], v10 offset:34560
	ds_read_b128 v[224:227], v10 offset:34816
	ds_read_b32 v228, v11 offset:33792
	ds_read_b128 v[230:233], v10 offset:35328
	v_add_f32_dpp v146, v146, v146 quad_perm:[1,0,3,2] row_mask:0xf bank_mask:0xf bound_ctrl:1
	v_pk_mul_f32 v[246:247], v[138:139], v[246:247]
	v_pk_fma_f32 v[246:247], v[140:141], v[248:249], v[246:247]
	v_add_f32_dpp v146, v146, v146 quad_perm:[2,3,0,1] row_mask:0xf bank_mask:0xf bound_ctrl:1
	s_waitcnt lgkmcnt(12)
	v_pk_mul_f32 v[176:177], v[176:177], v[184:185] op_sel_hi:[1,0]
	v_add_f32_dpp v146, v146, v146 row_half_mirror row_mask:0xf bank_mask:0xf bound_ctrl:1
	v_pk_mul_f32 v[178:179], v[178:179], v[184:185] op_sel_hi:[1,0]
	v_add_f32 v151, v246, v247
	v_add_f32_dpp v146, v146, v146 row_mirror row_mask:0xf bank_mask:0xf bound_ctrl:1
	v_pk_fma_f32 v[176:177], v[146:147], v[168:169], v[176:177] op_sel_hi:[0,1,1] neg_lo:[1,0,0] neg_hi:[1,0,0]
	v_pk_fma_f32 v[178:179], v[146:147], v[170:171], v[178:179] op_sel_hi:[0,1,1] neg_lo:[1,0,0] neg_hi:[1,0,0]
	v_pk_fma_f32 v[138:139], v[138:139], v[172:173], v[176:177]
	v_pk_fma_f32 v[140:141], v[140:141], v[174:175], v[178:179]
	v_pk_mul_f32 v[144:145], v[138:139], v[186:187]
	v_pk_fma_f32 v[144:145], v[140:141], v[188:189], v[144:145]
	v_add_f32 v146, v144, v145
	ds_read_b128 v[234:237], v10 offset:35584
	ds_read_b128 v[238:241], v10 offset:35840
	ds_read_b128 v[242:245], v10 offset:36096
	ds_read_b128 v[246:249], v10 offset:36352
	ds_read_b32 v250, v11 offset:35328
	ds_read_b128 v[164:167], v10 offset:36864
	v_add_f32_dpp v146, v146, v146 quad_perm:[1,0,3,2] row_mask:0xf bank_mask:0xf bound_ctrl:1
	v_pk_mul_f32 v[180:181], v[138:139], v[180:181]
	v_pk_fma_f32 v[180:181], v[140:141], v[182:183], v[180:181]
	v_add_f32_dpp v146, v146, v146 quad_perm:[2,3,0,1] row_mask:0xf bank_mask:0xf bound_ctrl:1
	s_waitcnt lgkmcnt(12)
	v_pk_mul_f32 v[198:199], v[198:199], v[206:207] op_sel_hi:[1,0]
	v_add_f32_dpp v146, v146, v146 row_half_mirror row_mask:0xf bank_mask:0xf bound_ctrl:1
	v_pk_mul_f32 v[200:201], v[200:201], v[206:207] op_sel_hi:[1,0]
	v_add_f32 v152, v180, v181
	v_add_f32_dpp v146, v146, v146 row_mirror row_mask:0xf bank_mask:0xf bound_ctrl:1
	v_pk_fma_f32 v[198:199], v[146:147], v[190:191], v[198:199] op_sel_hi:[0,1,1] neg_lo:[1,0,0] neg_hi:[1,0,0]
	v_pk_fma_f32 v[200:201], v[146:147], v[192:193], v[200:201] op_sel_hi:[0,1,1] neg_lo:[1,0,0] neg_hi:[1,0,0]
	v_pk_fma_f32 v[138:139], v[138:139], v[194:195], v[198:199]
	v_pk_fma_f32 v[140:141], v[140:141], v[196:197], v[200:201]
	v_pk_mul_f32 v[144:145], v[138:139], v[208:209]
	v_pk_fma_f32 v[144:145], v[140:141], v[210:211], v[144:145]
	v_add_f32 v146, v144, v145
	ds_read_b128 v[168:171], v10 offset:37120
	ds_read_b128 v[172:175], v10 offset:37376
	ds_read_b128 v[176:179], v10 offset:37632
	ds_read_b128 v[180:183], v10 offset:37888
	ds_read_b32 v184, v11 offset:36864
	ds_read_b128 v[186:189], v10 offset:38400
	v_add_f32_dpp v146, v146, v146 quad_perm:[1,0,3,2] row_mask:0xf bank_mask:0xf bound_ctrl:1
	v_pk_mul_f32 v[202:203], v[138:139], v[202:203]
	v_pk_fma_f32 v[202:203], v[140:141], v[204:205], v[202:203]
	v_add_f32_dpp v146, v146, v146 quad_perm:[2,3,0,1] row_mask:0xf bank_mask:0xf bound_ctrl:1
	s_waitcnt lgkmcnt(12)
	v_pk_mul_f32 v[220:221], v[220:221], v[228:229] op_sel_hi:[1,0]
	v_add_f32_dpp v146, v146, v146 row_half_mirror row_mask:0xf bank_mask:0xf bound_ctrl:1
	v_pk_mul_f32 v[222:223], v[222:223], v[228:229] op_sel_hi:[1,0]
	v_add_f32 v153, v202, v203
	v_add_f32_dpp v146, v146, v146 row_mirror row_mask:0xf bank_mask:0xf bound_ctrl:1
	v_pk_fma_f32 v[220:221], v[146:147], v[212:213], v[220:221] op_sel_hi:[0,1,1] neg_lo:[1,0,0] neg_hi:[1,0,0]
	v_pk_fma_f32 v[222:223], v[146:147], v[214:215], v[222:223] op_sel_hi:[0,1,1] neg_lo:[1,0,0] neg_hi:[1,0,0]
	v_pk_fma_f32 v[138:139], v[138:139], v[216:217], v[220:221]
	v_pk_fma_f32 v[140:141], v[140:141], v[218:219], v[222:223]
	v_pk_mul_f32 v[144:145], v[138:139], v[230:231]
	v_pk_fma_f32 v[144:145], v[140:141], v[232:233], v[144:145]
	v_add_f32 v146, v144, v145
	ds_read_b128 v[190:193], v10 offset:38656
	ds_read_b128 v[194:197], v10 offset:38912
	ds_read_b128 v[198:201], v10 offset:39168
	ds_read_b128 v[202:205], v10 offset:39424
	ds_read_b32 v206, v11 offset:38400
	ds_read_b128 v[208:211], v10 offset:39936
	v_add_f32_dpp v146, v146, v146 quad_perm:[1,0,3,2] row_mask:0xf bank_mask:0xf bound_ctrl:1
	v_pk_mul_f32 v[224:225], v[138:139], v[224:225]
	v_pk_fma_f32 v[224:225], v[140:141], v[226:227], v[224:225]
	v_add_f32_dpp v146, v146, v146 quad_perm:[2,3,0,1] row_mask:0xf bank_mask:0xf bound_ctrl:1
	s_waitcnt lgkmcnt(12)
	v_pk_mul_f32 v[242:243], v[242:243], v[250:251] op_sel_hi:[1,0]
	v_add_f32_dpp v146, v146, v146 row_half_mirror row_mask:0xf bank_mask:0xf bound_ctrl:1
	v_pk_mul_f32 v[244:245], v[244:245], v[250:251] op_sel_hi:[1,0]
	v_add_f32 v154, v224, v225
	v_add_f32_dpp v146, v146, v146 row_mirror row_mask:0xf bank_mask:0xf bound_ctrl:1
	v_pk_fma_f32 v[242:243], v[146:147], v[234:235], v[242:243] op_sel_hi:[0,1,1] neg_lo:[1,0,0] neg_hi:[1,0,0]
	v_pk_fma_f32 v[244:245], v[146:147], v[236:237], v[244:245] op_sel_hi:[0,1,1] neg_lo:[1,0,0] neg_hi:[1,0,0]
	v_pk_fma_f32 v[138:139], v[138:139], v[238:239], v[242:243]
	v_pk_fma_f32 v[140:141], v[140:141], v[240:241], v[244:245]
	v_pk_mul_f32 v[144:145], v[138:139], v[164:165]
	v_pk_fma_f32 v[144:145], v[140:141], v[166:167], v[144:145]
	v_add_f32 v146, v144, v145
	ds_read_b128 v[212:215], v10 offset:40192
	ds_read_b128 v[216:219], v10 offset:40448
	ds_read_b128 v[220:223], v10 offset:40704
	ds_read_b128 v[224:227], v10 offset:40960
	ds_read_b32 v228, v11 offset:39936
	ds_read_b128 v[230:233], v10 offset:41472
	v_add_f32_dpp v146, v146, v146 quad_perm:[1,0,3,2] row_mask:0xf bank_mask:0xf bound_ctrl:1
	v_pk_mul_f32 v[246:247], v[138:139], v[246:247]
	v_pk_fma_f32 v[246:247], v[140:141], v[248:249], v[246:247]
	v_add_f32_dpp v146, v146, v146 quad_perm:[2,3,0,1] row_mask:0xf bank_mask:0xf bound_ctrl:1
	s_waitcnt lgkmcnt(12)
	v_pk_mul_f32 v[176:177], v[176:177], v[184:185] op_sel_hi:[1,0]
	v_add_f32_dpp v146, v146, v146 row_half_mirror row_mask:0xf bank_mask:0xf bound_ctrl:1
	v_pk_mul_f32 v[178:179], v[178:179], v[184:185] op_sel_hi:[1,0]
	v_add_f32 v155, v246, v247
	v_add_f32_dpp v146, v146, v146 row_mirror row_mask:0xf bank_mask:0xf bound_ctrl:1
	v_pk_fma_f32 v[176:177], v[146:147], v[168:169], v[176:177] op_sel_hi:[0,1,1] neg_lo:[1,0,0] neg_hi:[1,0,0]
	v_pk_fma_f32 v[178:179], v[146:147], v[170:171], v[178:179] op_sel_hi:[0,1,1] neg_lo:[1,0,0] neg_hi:[1,0,0]
	v_pk_fma_f32 v[138:139], v[138:139], v[172:173], v[176:177]
	v_pk_fma_f32 v[140:141], v[140:141], v[174:175], v[178:179]
	v_pk_mul_f32 v[144:145], v[138:139], v[186:187]
	v_pk_fma_f32 v[144:145], v[140:141], v[188:189], v[144:145]
	v_add_f32 v146, v144, v145
	ds_read_b128 v[234:237], v10 offset:41728
	ds_read_b128 v[238:241], v10 offset:41984
	ds_read_b128 v[242:245], v10 offset:42240
	ds_read_b128 v[246:249], v10 offset:42496
	ds_read_b32 v250, v11 offset:41472
	ds_read_b128 v[164:167], v10 offset:43008
	v_add_f32_dpp v146, v146, v146 quad_perm:[1,0,3,2] row_mask:0xf bank_mask:0xf bound_ctrl:1
	v_pk_mul_f32 v[180:181], v[138:139], v[180:181]
	v_pk_fma_f32 v[180:181], v[140:141], v[182:183], v[180:181]
	v_add_f32_dpp v146, v146, v146 quad_perm:[2,3,0,1] row_mask:0xf bank_mask:0xf bound_ctrl:1
	s_waitcnt lgkmcnt(12)
	v_pk_mul_f32 v[198:199], v[198:199], v[206:207] op_sel_hi:[1,0]
	v_add_f32_dpp v146, v146, v146 row_half_mirror row_mask:0xf bank_mask:0xf bound_ctrl:1
	v_pk_mul_f32 v[200:201], v[200:201], v[206:207] op_sel_hi:[1,0]
	v_add_f32 v156, v180, v181
	v_add_f32_dpp v146, v146, v146 row_mirror row_mask:0xf bank_mask:0xf bound_ctrl:1
	v_pk_fma_f32 v[198:199], v[146:147], v[190:191], v[198:199] op_sel_hi:[0,1,1] neg_lo:[1,0,0] neg_hi:[1,0,0]
	v_pk_fma_f32 v[200:201], v[146:147], v[192:193], v[200:201] op_sel_hi:[0,1,1] neg_lo:[1,0,0] neg_hi:[1,0,0]
	v_pk_fma_f32 v[138:139], v[138:139], v[194:195], v[198:199]
	v_pk_fma_f32 v[140:141], v[140:141], v[196:197], v[200:201]
	v_pk_mul_f32 v[144:145], v[138:139], v[208:209]
	v_pk_fma_f32 v[144:145], v[140:141], v[210:211], v[144:145]
	v_add_f32 v146, v144, v145
	ds_read_b128 v[168:171], v10 offset:43264
	ds_read_b128 v[172:175], v10 offset:43520
	ds_read_b128 v[176:179], v10 offset:43776
	ds_read_b128 v[180:183], v10 offset:44032
	ds_read_b32 v184, v11 offset:43008
	ds_read_b128 v[186:189], v10 offset:44544
	v_add_f32_dpp v146, v146, v146 quad_perm:[1,0,3,2] row_mask:0xf bank_mask:0xf bound_ctrl:1
	v_pk_mul_f32 v[202:203], v[138:139], v[202:203]
	v_pk_fma_f32 v[202:203], v[140:141], v[204:205], v[202:203]
	v_add_f32_dpp v146, v146, v146 quad_perm:[2,3,0,1] row_mask:0xf bank_mask:0xf bound_ctrl:1
	s_waitcnt lgkmcnt(12)
	v_pk_mul_f32 v[220:221], v[220:221], v[228:229] op_sel_hi:[1,0]
	v_add_f32_dpp v146, v146, v146 row_half_mirror row_mask:0xf bank_mask:0xf bound_ctrl:1
	v_pk_mul_f32 v[222:223], v[222:223], v[228:229] op_sel_hi:[1,0]
	v_add_f32 v157, v202, v203
	v_add_f32_dpp v146, v146, v146 row_mirror row_mask:0xf bank_mask:0xf bound_ctrl:1
	v_pk_fma_f32 v[220:221], v[146:147], v[212:213], v[220:221] op_sel_hi:[0,1,1] neg_lo:[1,0,0] neg_hi:[1,0,0]
	v_pk_fma_f32 v[222:223], v[146:147], v[214:215], v[222:223] op_sel_hi:[0,1,1] neg_lo:[1,0,0] neg_hi:[1,0,0]
	v_pk_fma_f32 v[138:139], v[138:139], v[216:217], v[220:221]
	v_pk_fma_f32 v[140:141], v[140:141], v[218:219], v[222:223]
	v_pk_mul_f32 v[144:145], v[138:139], v[230:231]
	v_pk_fma_f32 v[144:145], v[140:141], v[232:233], v[144:145]
	v_add_f32 v146, v144, v145
	ds_read_b128 v[190:193], v10 offset:44800
	ds_read_b128 v[194:197], v10 offset:45056
	ds_read_b128 v[198:201], v10 offset:45312
	ds_read_b128 v[202:205], v10 offset:45568
	ds_read_b32 v206, v11 offset:44544
	ds_read_b128 v[208:211], v10 offset:46080
	v_add_f32_dpp v146, v146, v146 quad_perm:[1,0,3,2] row_mask:0xf bank_mask:0xf bound_ctrl:1
	v_pk_mul_f32 v[224:225], v[138:139], v[224:225]
	v_pk_fma_f32 v[224:225], v[140:141], v[226:227], v[224:225]
	v_add_f32_dpp v146, v146, v146 quad_perm:[2,3,0,1] row_mask:0xf bank_mask:0xf bound_ctrl:1
	s_waitcnt lgkmcnt(12)
	v_pk_mul_f32 v[242:243], v[242:243], v[250:251] op_sel_hi:[1,0]
	v_add_f32_dpp v146, v146, v146 row_half_mirror row_mask:0xf bank_mask:0xf bound_ctrl:1
	v_pk_mul_f32 v[244:245], v[244:245], v[250:251] op_sel_hi:[1,0]
	v_add_f32 v158, v224, v225
	v_add_f32_dpp v146, v146, v146 row_mirror row_mask:0xf bank_mask:0xf bound_ctrl:1
	v_pk_fma_f32 v[242:243], v[146:147], v[234:235], v[242:243] op_sel_hi:[0,1,1] neg_lo:[1,0,0] neg_hi:[1,0,0]
	v_pk_fma_f32 v[244:245], v[146:147], v[236:237], v[244:245] op_sel_hi:[0,1,1] neg_lo:[1,0,0] neg_hi:[1,0,0]
	v_pk_fma_f32 v[138:139], v[138:139], v[238:239], v[242:243]
	v_pk_fma_f32 v[140:141], v[140:141], v[240:241], v[244:245]
	v_pk_mul_f32 v[144:145], v[138:139], v[164:165]
	v_pk_fma_f32 v[144:145], v[140:141], v[166:167], v[144:145]
	v_add_f32 v146, v144, v145
	ds_read_b128 v[212:215], v10 offset:46336
	ds_read_b128 v[216:219], v10 offset:46592
	ds_read_b128 v[220:223], v10 offset:46848
	ds_read_b128 v[224:227], v10 offset:47104
	ds_read_b32 v228, v11 offset:46080
	ds_read_b128 v[230:233], v10 offset:47616
	v_add_f32_dpp v146, v146, v146 quad_perm:[1,0,3,2] row_mask:0xf bank_mask:0xf bound_ctrl:1
	v_pk_mul_f32 v[246:247], v[138:139], v[246:247]
	v_pk_fma_f32 v[246:247], v[140:141], v[248:249], v[246:247]
	v_add_f32_dpp v146, v146, v146 quad_perm:[2,3,0,1] row_mask:0xf bank_mask:0xf bound_ctrl:1
	s_waitcnt lgkmcnt(12)
	v_pk_mul_f32 v[176:177], v[176:177], v[184:185] op_sel_hi:[1,0]
	v_add_f32_dpp v146, v146, v146 row_half_mirror row_mask:0xf bank_mask:0xf bound_ctrl:1
	v_pk_mul_f32 v[178:179], v[178:179], v[184:185] op_sel_hi:[1,0]
	v_add_f32 v159, v246, v247
	v_add_f32_dpp v146, v146, v146 row_mirror row_mask:0xf bank_mask:0xf bound_ctrl:1
	v_pk_fma_f32 v[176:177], v[146:147], v[168:169], v[176:177] op_sel_hi:[0,1,1] neg_lo:[1,0,0] neg_hi:[1,0,0]
	v_pk_fma_f32 v[178:179], v[146:147], v[170:171], v[178:179] op_sel_hi:[0,1,1] neg_lo:[1,0,0] neg_hi:[1,0,0]
	v_pk_fma_f32 v[138:139], v[138:139], v[172:173], v[176:177]
	v_pk_fma_f32 v[140:141], v[140:141], v[174:175], v[178:179]
	v_pk_mul_f32 v[144:145], v[138:139], v[186:187]
	v_pk_fma_f32 v[144:145], v[140:141], v[188:189], v[144:145]
	v_add_f32 v146, v144, v145
	ds_read_b128 v[234:237], v10 offset:47872
	ds_read_b128 v[238:241], v10 offset:48128
	ds_read_b128 v[242:245], v10 offset:48384
	ds_read_b128 v[246:249], v10 offset:48640
	ds_read_b32 v250, v11 offset:47616
	v_add_f32_dpp v146, v146, v146 quad_perm:[1,0,3,2] row_mask:0xf bank_mask:0xf bound_ctrl:1
	v_pk_mul_f32 v[180:181], v[138:139], v[180:181]
	v_pk_fma_f32 v[180:181], v[140:141], v[182:183], v[180:181]
	v_add_f32_dpp v146, v146, v146 quad_perm:[2,3,0,1] row_mask:0xf bank_mask:0xf bound_ctrl:1
	s_waitcnt lgkmcnt(11)
	v_pk_mul_f32 v[198:199], v[198:199], v[206:207] op_sel_hi:[1,0]
	v_add_f32_dpp v146, v146, v146 row_half_mirror row_mask:0xf bank_mask:0xf bound_ctrl:1
	v_pk_mul_f32 v[200:201], v[200:201], v[206:207] op_sel_hi:[1,0]
	v_add_f32 v160, v180, v181
	v_add_f32_dpp v146, v146, v146 row_mirror row_mask:0xf bank_mask:0xf bound_ctrl:1
	v_pk_fma_f32 v[198:199], v[146:147], v[190:191], v[198:199] op_sel_hi:[0,1,1] neg_lo:[1,0,0] neg_hi:[1,0,0]
	v_pk_fma_f32 v[200:201], v[146:147], v[192:193], v[200:201] op_sel_hi:[0,1,1] neg_lo:[1,0,0] neg_hi:[1,0,0]
	v_pk_fma_f32 v[138:139], v[138:139], v[194:195], v[198:199]
	v_pk_fma_f32 v[140:141], v[140:141], v[196:197], v[200:201]
	v_pk_mul_f32 v[144:145], v[138:139], v[208:209]
	v_pk_fma_f32 v[144:145], v[140:141], v[210:211], v[144:145]
	v_add_f32 v146, v144, v145
	s_nop 1
	v_add_f32_dpp v146, v146, v146 quad_perm:[1,0,3,2] row_mask:0xf bank_mask:0xf bound_ctrl:1
	v_pk_mul_f32 v[202:203], v[138:139], v[202:203]
	v_pk_fma_f32 v[202:203], v[140:141], v[204:205], v[202:203]
	v_add_f32_dpp v146, v146, v146 quad_perm:[2,3,0,1] row_mask:0xf bank_mask:0xf bound_ctrl:1
	s_waitcnt lgkmcnt(5)
	v_pk_mul_f32 v[220:221], v[220:221], v[228:229] op_sel_hi:[1,0]
	v_add_f32_dpp v146, v146, v146 row_half_mirror row_mask:0xf bank_mask:0xf bound_ctrl:1
	v_pk_mul_f32 v[222:223], v[222:223], v[228:229] op_sel_hi:[1,0]
	v_add_f32 v161, v202, v203
	v_add_f32_dpp v146, v146, v146 row_mirror row_mask:0xf bank_mask:0xf bound_ctrl:1
	v_pk_fma_f32 v[220:221], v[146:147], v[212:213], v[220:221] op_sel_hi:[0,1,1] neg_lo:[1,0,0] neg_hi:[1,0,0]
	v_pk_fma_f32 v[222:223], v[146:147], v[214:215], v[222:223] op_sel_hi:[0,1,1] neg_lo:[1,0,0] neg_hi:[1,0,0]
	v_pk_fma_f32 v[138:139], v[138:139], v[216:217], v[220:221]
	v_pk_fma_f32 v[140:141], v[140:141], v[218:219], v[222:223]
	v_pk_mul_f32 v[144:145], v[138:139], v[230:231]
	v_pk_fma_f32 v[144:145], v[140:141], v[232:233], v[144:145]
	v_add_f32 v146, v144, v145
	s_nop 1
	v_add_f32_dpp v146, v146, v146 quad_perm:[1,0,3,2] row_mask:0xf bank_mask:0xf bound_ctrl:1
	v_pk_mul_f32 v[224:225], v[138:139], v[224:225]
	v_pk_fma_f32 v[224:225], v[140:141], v[226:227], v[224:225]
	v_add_f32_dpp v146, v146, v146 quad_perm:[2,3,0,1] row_mask:0xf bank_mask:0xf bound_ctrl:1
	s_waitcnt lgkmcnt(0)
	v_pk_mul_f32 v[242:243], v[242:243], v[250:251] op_sel_hi:[1,0]
	v_add_f32_dpp v146, v146, v146 row_half_mirror row_mask:0xf bank_mask:0xf bound_ctrl:1
	v_pk_mul_f32 v[244:245], v[244:245], v[250:251] op_sel_hi:[1,0]
	v_add_f32 v162, v224, v225
	v_add_f32_dpp v146, v146, v146 row_mirror row_mask:0xf bank_mask:0xf bound_ctrl:1
	v_pk_fma_f32 v[242:243], v[146:147], v[234:235], v[242:243] op_sel_hi:[0,1,1] neg_lo:[1,0,0] neg_hi:[1,0,0]
	v_pk_fma_f32 v[244:245], v[146:147], v[236:237], v[244:245] op_sel_hi:[0,1,1] neg_lo:[1,0,0] neg_hi:[1,0,0]
	v_pk_fma_f32 v[138:139], v[138:139], v[238:239], v[242:243]
	v_pk_fma_f32 v[140:141], v[140:141], v[240:241], v[244:245]
	v_pk_mul_f32 v[246:247], v[138:139], v[246:247]
	v_pk_fma_f32 v[246:247], v[140:141], v[248:249], v[246:247]
	v_add_f32 v163, v246, v247
	s_nop 0
	v_add_f32_dpp v102, v148, v148 row_mirror row_mask:0xf bank_mask:0x3 bound_ctrl:1
	v_add_f32_dpp v102, v156, v156 row_mirror row_mask:0xf bank_mask:0xc bound_ctrl:1
	v_add_f32_dpp v103, v149, v149 row_mirror row_mask:0xf bank_mask:0x3 bound_ctrl:1
	v_add_f32_dpp v103, v157, v157 row_mirror row_mask:0xf bank_mask:0xc bound_ctrl:1
	v_add_f32_dpp v104, v150, v150 row_mirror row_mask:0xf bank_mask:0x3 bound_ctrl:1
	v_add_f32_dpp v104, v158, v158 row_mirror row_mask:0xf bank_mask:0xc bound_ctrl:1
	v_add_f32_dpp v105, v151, v151 row_mirror row_mask:0xf bank_mask:0x3 bound_ctrl:1
	v_add_f32_dpp v105, v159, v159 row_mirror row_mask:0xf bank_mask:0xc bound_ctrl:1
	v_add_f32_dpp v106, v152, v152 row_mirror row_mask:0xf bank_mask:0x3 bound_ctrl:1
	v_add_f32_dpp v106, v160, v160 row_mirror row_mask:0xf bank_mask:0xc bound_ctrl:1
	v_add_f32_dpp v107, v153, v153 row_mirror row_mask:0xf bank_mask:0x3 bound_ctrl:1
	v_add_f32_dpp v107, v161, v161 row_mirror row_mask:0xf bank_mask:0xc bound_ctrl:1
	v_add_f32_dpp v108, v154, v154 row_mirror row_mask:0xf bank_mask:0x3 bound_ctrl:1
	v_add_f32_dpp v108, v162, v162 row_mirror row_mask:0xf bank_mask:0xc bound_ctrl:1
	v_add_f32_dpp v109, v155, v155 row_mirror row_mask:0xf bank_mask:0x3 bound_ctrl:1
	v_add_f32_dpp v109, v163, v163 row_mirror row_mask:0xf bank_mask:0xc bound_ctrl:1
	v_add_f32_dpp v110, v102, v102 row_half_mirror row_mask:0xf bank_mask:0x5 bound_ctrl:1
	v_add_f32_dpp v110, v106, v106 row_half_mirror row_mask:0xf bank_mask:0xa bound_ctrl:1
	v_add_f32_dpp v111, v103, v103 row_half_mirror row_mask:0xf bank_mask:0x5 bound_ctrl:1
	v_add_f32_dpp v111, v107, v107 row_half_mirror row_mask:0xf bank_mask:0xa bound_ctrl:1
	v_add_f32_dpp v112, v104, v104 row_half_mirror row_mask:0xf bank_mask:0x5 bound_ctrl:1
	v_add_f32_dpp v112, v108, v108 row_half_mirror row_mask:0xf bank_mask:0xa bound_ctrl:1
	v_add_f32_dpp v113, v105, v105 row_half_mirror row_mask:0xf bank_mask:0x5 bound_ctrl:1
	v_add_f32_dpp v113, v109, v109 row_half_mirror row_mask:0xf bank_mask:0xa bound_ctrl:1
	s_mov_b32 vcc_lo, 0xcccccccc
	s_mov_b32 vcc_hi, 0xcccccccc
	v_cndmask_b32 v116, v112, v110, vcc
	v_cndmask_b32 v117, v113, v111, vcc
	v_cndmask_b32 v114, v110, v112, vcc
	v_cndmask_b32 v115, v111, v113, vcc
	v_add_f32_dpp v114, v116, v114 quad_perm:[2,3,0,1] row_mask:0xf bank_mask:0xf bound_ctrl:1
	v_add_f32_dpp v115, v117, v115 quad_perm:[2,3,0,1] row_mask:0xf bank_mask:0xf bound_ctrl:1
	s_mov_b32 vcc_lo, 0xaaaaaaaa
	s_mov_b32 vcc_hi, 0xaaaaaaaa
	v_cndmask_b32 v116, v115, v114, vcc
	v_cndmask_b32 v117, v114, v115, vcc
	s_nop 0
	v_add_f32_dpp v19, v116, v117 quad_perm:[1,0,3,2] row_mask:0xf bank_mask:0xf bound_ctrl:1

; #define SCAN_BAR() asm volatile("s_barrier" ::: "memory")
; __device__ __forceinline__ void scan_unit(const Ctx& C0, const float* scn, int T, int quarter, const float* S0, float* Sout, unsigned char* obase, int mode) {
;     ...
;             if (mode == 0) { *(float*)(obase + (size_t)(k * 32 + q) * UPITCH_B + rl * 4) = osel0; *(float*)(obase + (size_t)(k * 32 + 16 + q) * UPITCH_B + rl * 4) = osel1; }
;             SCAN_BAR();
;         }
;         if (mode == 0) *(f32x4*)(Sout + irow * 64 + 4 * q) = (f32x4){S0x, S1x, S2x, S3x};
	s_addc_u32 s1, s1, 0
	v_add_co_u32_e32 v16, vcc, s8, v14
	s_cmp_lg_u32 s0, 0x5600000
	s_nop 0
	v_addc_co_u32_e32 v17, vcc, 0, v15, vcc
	v_add_co_u32_e32 v14, vcc, 0xfcaa000, v14
	global_store_dword v[16:17], v18, off offset:768
	s_nop 0
	v_addc_co_u32_e32 v15, vcc, 0, v15, vcc
	global_store_dword v[14:15], v19, off offset:768
	s_barrier
	s_cbranch_scc1 .LBB0_685
	v_mov_b32_e32 v2, v138
	v_mov_b32_e32 v13, v139
	v_mov_b32_e32 v12, v140
	v_mov_b32_e32 v8, v141
	v_readlane_b32 s0, v255, 46
	s_add_i32 s0, s3, s0
	s_ashr_i32 s1, s0, 31
	s_lshl_b64 s[0:1], s[0:1], 17
	v_readlane_b32 s3, v253, 26
	s_add_u32 s0, s3, s0
	v_readlane_b32 s3, v253, 27
	s_addc_u32 s1, s3, s1
	s_lshl_b32 s2, s2, 14
	s_add_u32 s0, s0, s2
	s_addc_u32 s1, s1, 0
	v_lshlrev_b32_e32 v0, 8, v0
	v_lshl_add_u64 v[6:7], s[0:1], 0, v[0:1]
	v_mov_b32_e32 v5, v1
	v_lshl_add_u64 v[6:7], v[6:7], 0, v[4:5]
	v_mov_b32_e32 v3, v13
	v_mov_b32_e32 v4, v12
	v_mov_b32_e32 v5, v8
	global_store_dwordx4 v[6:7], v[2:5], off
